# diff-attention block epilogue rewritten by hand: O_0 hand-off as lane-major dwordx4 image (16 stores / 16 loads per lane instead of 128 dword ops), component-1 AO stores with all lanes (64 instead of
# speedup vs baseline: 1.0074x; 1.0074x over previous
.Lep_done:
	s_add_i32 s82, s82, 1
	s_add_u32 s54, s54, 64
	s_addc_u32 s55, s55, 0
	s_cmp_eq_u32 s82, 4
	s_cbranch_scc1 .LBB0_420

.LBB0_445:
	s_and_saveexec_b64 s[56:57], s[4:5]
	ds_write_b32 v247, v250
	s_or_b64 exec, exec, s[56:57]
	s_waitcnt lgkmcnt(0)
	s_movk_i32 s83, 0x800
	v_lshl_add_u32 v0, v211, 2, s21
	ds_read2_b32 v[2:3], v0 offset1:1
	s_add_u32 s0, s78, s6
	s_addc_u32 s4, s79, s7
	s_waitcnt lgkmcnt(0)
	v_rcp_f32_e32 v4, v2
	v_rcp_f32_e32 v150, v3
	ds_read2_b32 v[2:3], v0 offset0:2 offset1:3
	v_mul_f32_e32 v130, v130, v4
	v_mul_f32_e32 v114, v114, v4
	v_mul_f32_e32 v98, v98, v4
	s_waitcnt lgkmcnt(0)
	v_rcp_f32_e32 v149, v2
	v_rcp_f32_e32 v148, v3
	ds_read2_b32 v[2:3], v0 offset0:8 offset1:9
	v_mul_f32_e32 v82, v82, v4
	v_mul_f32_e32 v66, v66, v4
	v_mul_f32_e32 v50, v50, v4
	v_mul_f32_e32 v34, v34, v4
	s_waitcnt lgkmcnt(0)
	v_rcp_f32_e32 v147, v2
	v_rcp_f32_e32 v146, v3
	ds_read2_b32 v[2:3], v0 offset0:10 offset1:11
	v_mul_f32_e32 v18, v18, v4
	s_waitcnt lgkmcnt(0)
	v_rcp_f32_e32 v15, v2
	v_rcp_f32_e32 v14, v3
	ds_read2_b32 v[2:3], v0 offset0:16 offset1:17
	s_waitcnt lgkmcnt(0)
	v_rcp_f32_e32 v13, v2
	v_rcp_f32_e32 v12, v3
	ds_read2_b32 v[2:3], v0 offset0:18 offset1:19
	s_waitcnt lgkmcnt(0)
	v_rcp_f32_e32 v11, v2
	v_rcp_f32_e32 v10, v3
	ds_read2_b32 v[2:3], v0 offset0:24 offset1:25
	s_waitcnt lgkmcnt(0)
	v_rcp_f32_e32 v9, v2
	v_rcp_f32_e32 v8, v3
	ds_read2_b32 v[2:3], v0 offset0:26 offset1:27
	s_mul_hi_i32 s3, s83, s1
	s_mul_i32 s2, s83, s1
	s_lshl_b64 s[2:3], s[2:3], 1
	s_waitcnt lgkmcnt(0)
	v_rcp_f32_e32 v7, v2
	v_rcp_f32_e32 v6, v3
	s_add_u32 s56, s0, s2
	s_addc_u32 s57, s4, s3
	s_cmp_gt_u32 s82, 1
	s_cbranch_scc0 .Lep_mode0
	s_add_u32 s58, s80, s6
	s_addc_u32 s59, s81, s7
	s_mul_i32 s2, s83, s1
	s_lshl_b32 s2, s2, 1
	s_add_u32 s58, s58, s2
	s_addc_u32 s59, s59, 0
	v_and_b32_e32 v151, 1, v210
	v_cmp_eq_u32_e64 s[60:61], 0, v151
	v_lshlrev_b32_e32 v2, 2, v210
	global_load_dword v224, v2, s[46:47] offset:0
	global_load_dword v225, v2, s[46:47] offset:128
	global_load_dword v226, v2, s[46:47] offset:256
	global_load_dword v227, v2, s[46:47] offset:384
	global_load_dword v228, v2, s[46:47] offset:512
	global_load_dword v229, v2, s[46:47] offset:640
	global_load_dword v230, v2, s[46:47] offset:768
	global_load_dword v231, v2, s[46:47] offset:896
	v_lshlrev_b32_e32 v3, 12, v237
	v_lshl_add_u32 v3, v210, 4, v3
	global_load_dwordx4 v[152:155], v3, s[56:57] sc1
	v_add_u32_e32 v3, 0x2000, v3
	global_load_dwordx4 v[156:159], v3, s[56:57] sc1
	v_add_u32_e32 v3, 0x2000, v3
	global_load_dwordx4 v[160:163], v3, s[56:57] sc1
	v_add_u32_e32 v3, 0x2000, v3
	global_load_dwordx4 v[164:167], v3, s[56:57] sc1
	v_add_u32_e32 v3, 0x2000, v3
	global_load_dwordx4 v[168:171], v3, s[56:57] sc1
	v_add_u32_e32 v3, 0x2000, v3
	global_load_dwordx4 v[172:175], v3, s[56:57] sc1
	v_add_u32_e32 v3, 0x2000, v3
	global_load_dwordx4 v[176:179], v3, s[56:57] sc1
	v_add_u32_e32 v3, 0x2000, v3
	global_load_dwordx4 v[180:183], v3, s[56:57] sc1
	v_add_u32_e32 v3, 0x2000, v3
	global_load_dwordx4 v[184:187], v3, s[56:57] sc1
	v_add_u32_e32 v3, 0x2000, v3
	global_load_dwordx4 v[188:191], v3, s[56:57] sc1
	v_add_u32_e32 v3, 0x2000, v3
	global_load_dwordx4 v[192:195], v3, s[56:57] sc1
	v_add_u32_e32 v3, 0x2000, v3
	global_load_dwordx4 v[196:199], v3, s[56:57] sc1
	v_add_u32_e32 v3, 0x2000, v3
	global_load_dwordx4 v[200:203], v3, s[56:57] sc1
	v_add_u32_e32 v3, 0x2000, v3
	global_load_dwordx4 v[204:207], v3, s[56:57] sc1
	v_add_u32_e32 v3, 0x2000, v3
	global_load_dwordx4 v[216:219], v3, s[56:57] sc1
	v_add_u32_e32 v3, 0x2000, v3
	global_load_dwordx4 v[220:223], v3, s[56:57] sc1
	v_lshlrev_b32_e32 v212, 2, v210
	v_lshlrev_b32_e32 v213, 7, v237
	v_xad_u32 v0, v212, 64, v213
	v_lshlrev_b32_e32 v212, 14, v237
	v_lshl_add_u32 v212, v210, 1, v212
	v_mul_u32_u24_e32 v213, 62, v151
	v_add_u32_e32 v212, v212, v213
	s_waitcnt vmcnt(16)
	v_mul_f32_e32 v224, v236, v224
	v_mul_f32_e32 v225, v236, v225
	v_mul_f32_e32 v226, v236, v226
	v_mul_f32_e32 v227, v236, v227
	v_mul_f32_e32 v228, v236, v228
	v_mul_f32_e32 v229, v236, v229
	v_mul_f32_e32 v230, v236, v230
	v_mul_f32_e32 v231, v236, v231
	s_waitcnt vmcnt(15)
	v_lshlrev_b32_e32 v250, 16, v152
	v_fma_f32 v240, -v17, v130, v250
	v_and_b32_e32 v250, 0xffff0000, v152
	v_fma_f32 v241, -v17, v114, v250
	v_lshlrev_b32_e32 v250, 16, v153
	v_fma_f32 v242, -v17, v98, v250
	v_and_b32_e32 v250, 0xffff0000, v153
	v_fma_f32 v243, -v17, v82, v250
	v_lshlrev_b32_e32 v250, 16, v154
	v_fma_f32 v245, -v17, v66, v250
	v_and_b32_e32 v250, 0xffff0000, v154
	v_fma_f32 v246, -v17, v50, v250
	v_lshlrev_b32_e32 v250, 16, v155
	v_fma_f32 v247, -v17, v34, v250
	v_and_b32_e32 v250, 0xffff0000, v155
	v_fma_f32 v248, -v17, v18, v250
	v_mul_f32_e32 v251, v241, v241
	v_fmac_f32_e32 v251, v240, v240
	v_fmac_f32_e32 v251, v242, v242
	v_fmac_f32_e32 v251, v243, v243
	v_fmac_f32_e32 v251, v245, v245
	v_fmac_f32_e32 v251, v246, v246
	v_fmac_f32_e32 v251, v247, v247
	v_fmac_f32_e32 v251, v248, v248
	s_nop 1
	v_add_f32_dpp v251, v251, v251 quad_perm:[1,0,3,2] row_mask:0xf bank_mask:0xf bound_ctrl:1
	s_nop 1
	v_add_f32_dpp v251, v251, v251 quad_perm:[2,3,0,1] row_mask:0xf bank_mask:0xf bound_ctrl:1
	s_nop 1
	v_add_f32_dpp v251, v251, v251 row_half_mirror row_mask:0xf bank_mask:0xf bound_ctrl:1
	s_nop 1
	v_add_f32_dpp v251, v251, v251 row_mirror row_mask:0xf bank_mask:0xf bound_ctrl:1
	ds_bpermute_b32 v252, v0, v251
	s_waitcnt lgkmcnt(0)
	v_add_f32_e32 v251, v251, v252
	v_fmamk_f32 v251, v251, 0x3b800000, v238
	v_mul_f32_e32 v252, 0x4f800000, v251
	v_cmp_gt_f32_e32 vcc, s24, v251
	s_nop 1
	v_cndmask_b32_e32 v251, v251, v252, vcc
	v_sqrt_f32_e32 v252, v251
	s_nop 0
	v_add_u32_e32 v249, -1, v252
	v_fma_f32 v250, -v249, v252, v251
	v_cmp_ge_f32_e64 s[6:7], 0, v250
	v_add_u32_e32 v250, 1, v252
	s_nop 0
	v_cndmask_b32_e64 v249, v252, v249, s[6:7]
	v_fma_f32 v252, -v250, v252, v251
	v_cmp_lt_f32_e64 s[6:7], 0, v252
	s_nop 1
	v_cndmask_b32_e64 v252, v249, v250, s[6:7]
	v_mul_f32_e32 v249, 0x37800000, v252
	v_cndmask_b32_e32 v252, v252, v249, vcc
	v_cmp_class_f32_e32 vcc, v251, v239
	s_nop 1
	v_cndmask_b32_e32 v251, v252, v251, vcc
	v_div_scale_f32 v252, s[2:3], v251, v251, 1.0
	v_rcp_f32_e32 v249, v252
	s_nop 0
	v_fma_f32 v250, -v252, v249, 1.0
	v_fmac_f32_e32 v249, v250, v249
	v_div_scale_f32 v250, vcc, 1.0, v251, 1.0
	v_mul_f32_e32 v253, v250, v249
	v_fma_f32 v213, -v252, v253, v250
	v_fmac_f32_e32 v253, v213, v249
	v_fma_f32 v252, -v252, v253, v250
	v_div_fmas_f32 v252, v252, v249, v253
	v_div_fixup_f32 v253, v252, v251, 1.0
	v_mul_f32_e32 v240, v240, v253
	v_mul_f32_e32 v241, v241, v253
	v_mul_f32_e32 v242, v242, v253
	v_mul_f32_e32 v243, v243, v253
	v_mul_f32_e32 v245, v245, v253
	v_mul_f32_e32 v246, v246, v253
	v_mul_f32_e32 v247, v247, v253
	v_mul_f32_e32 v248, v248, v253
	v_mul_f32_e32 v240, v224, v240
	v_mul_f32_e32 v241, v225, v241
	v_mul_f32_e32 v242, v226, v242
	v_mul_f32_e32 v243, v227, v243
	v_mul_f32_e32 v245, v228, v245
	v_mul_f32_e32 v246, v229, v246
	v_mul_f32_e32 v247, v230, v247
	v_mul_f32_e32 v248, v231, v248
	v_add_u32_e32 v249, 0x0, v212
	v_mov_b32_dpp v232, v240 quad_perm:[1,0,3,2] row_mask:0xf bank_mask:0xf bound_ctrl:1
	v_mov_b32_dpp v233, v241 quad_perm:[1,0,3,2] row_mask:0xf bank_mask:0xf bound_ctrl:1
	v_mov_b32_dpp v234, v242 quad_perm:[1,0,3,2] row_mask:0xf bank_mask:0xf bound_ctrl:1
	v_mov_b32_dpp v235, v243 quad_perm:[1,0,3,2] row_mask:0xf bank_mask:0xf bound_ctrl:1
	v_mov_b32_dpp v2, v245 quad_perm:[1,0,3,2] row_mask:0xf bank_mask:0xf bound_ctrl:1
	v_mov_b32_dpp v3, v246 quad_perm:[1,0,3,2] row_mask:0xf bank_mask:0xf bound_ctrl:1
	v_mov_b32_dpp v5, v247 quad_perm:[1,0,3,2] row_mask:0xf bank_mask:0xf bound_ctrl:1
	v_mov_b32_dpp v151, v248 quad_perm:[1,0,3,2] row_mask:0xf bank_mask:0xf bound_ctrl:1
	v_cvt_pk_bf16_f32 v232, v240, v232
	v_cvt_pk_bf16_f32 v233, v233, v241
	v_cndmask_b32_e64 v232, v233, v232, s[60:61]
	global_store_dword v249, v232, s[58:59] offset:0
	v_cvt_pk_bf16_f32 v234, v242, v234
	v_cvt_pk_bf16_f32 v235, v235, v243
	v_cndmask_b32_e64 v234, v235, v234, s[60:61]
	global_store_dword v249, v234, s[58:59] offset:128
	v_cvt_pk_bf16_f32 v2, v245, v2
	v_cvt_pk_bf16_f32 v3, v3, v246
	v_cndmask_b32_e64 v2, v3, v2, s[60:61]
	global_store_dword v249, v2, s[58:59] offset:256
	v_cvt_pk_bf16_f32 v5, v247, v5
	v_cvt_pk_bf16_f32 v151, v151, v248
	v_cndmask_b32_e64 v5, v151, v5, s[60:61]
	global_store_dword v249, v5, s[58:59] offset:384
	s_waitcnt vmcnt(18)
	v_lshlrev_b32_e32 v250, 16, v156
	v_mul_f32_e32 v249, v131, v150
	v_fma_f32 v240, -v17, v249, v250
	v_and_b32_e32 v250, 0xffff0000, v156
	v_mul_f32_e32 v249, v115, v150
	v_fma_f32 v241, -v17, v249, v250
	v_lshlrev_b32_e32 v250, 16, v157
	v_mul_f32_e32 v249, v99, v150
	v_fma_f32 v242, -v17, v249, v250
	v_and_b32_e32 v250, 0xffff0000, v157
	v_mul_f32_e32 v249, v83, v150
	v_fma_f32 v243, -v17, v249, v250
	v_lshlrev_b32_e32 v250, 16, v158
	v_mul_f32_e32 v249, v67, v150
	v_fma_f32 v245, -v17, v249, v250
	v_and_b32_e32 v250, 0xffff0000, v158
	v_mul_f32_e32 v249, v51, v150
	v_fma_f32 v246, -v17, v249, v250
	v_lshlrev_b32_e32 v250, 16, v159
	v_mul_f32_e32 v249, v35, v150
	v_fma_f32 v247, -v17, v249, v250
	v_and_b32_e32 v250, 0xffff0000, v159
	v_mul_f32_e32 v249, v19, v150
	v_fma_f32 v248, -v17, v249, v250
	v_mul_f32_e32 v251, v241, v241
	v_fmac_f32_e32 v251, v240, v240
	v_fmac_f32_e32 v251, v242, v242
	v_fmac_f32_e32 v251, v243, v243
	v_fmac_f32_e32 v251, v245, v245
	v_fmac_f32_e32 v251, v246, v246
	v_fmac_f32_e32 v251, v247, v247
	v_fmac_f32_e32 v251, v248, v248
	s_nop 1
	v_add_f32_dpp v251, v251, v251 quad_perm:[1,0,3,2] row_mask:0xf bank_mask:0xf bound_ctrl:1
	s_nop 1
	v_add_f32_dpp v251, v251, v251 quad_perm:[2,3,0,1] row_mask:0xf bank_mask:0xf bound_ctrl:1
	s_nop 1
	v_add_f32_dpp v251, v251, v251 row_half_mirror row_mask:0xf bank_mask:0xf bound_ctrl:1
	s_nop 1
	v_add_f32_dpp v251, v251, v251 row_mirror row_mask:0xf bank_mask:0xf bound_ctrl:1
	ds_bpermute_b32 v252, v0, v251
	s_waitcnt lgkmcnt(0)
	v_add_f32_e32 v251, v251, v252
	v_fmamk_f32 v251, v251, 0x3b800000, v238
	v_mul_f32_e32 v252, 0x4f800000, v251
	v_cmp_gt_f32_e32 vcc, s24, v251
	s_nop 1
	v_cndmask_b32_e32 v251, v251, v252, vcc
	v_sqrt_f32_e32 v252, v251
	s_nop 0
	v_add_u32_e32 v249, -1, v252
	v_fma_f32 v250, -v249, v252, v251
	v_cmp_ge_f32_e64 s[6:7], 0, v250
	v_add_u32_e32 v250, 1, v252
	s_nop 0
	v_cndmask_b32_e64 v249, v252, v249, s[6:7]
	v_fma_f32 v252, -v250, v252, v251
	v_cmp_lt_f32_e64 s[6:7], 0, v252
	s_nop 1
	v_cndmask_b32_e64 v252, v249, v250, s[6:7]
	v_mul_f32_e32 v249, 0x37800000, v252
	v_cndmask_b32_e32 v252, v252, v249, vcc
	v_cmp_class_f32_e32 vcc, v251, v239
	s_nop 1
	v_cndmask_b32_e32 v251, v252, v251, vcc
	v_div_scale_f32 v252, s[2:3], v251, v251, 1.0
	v_rcp_f32_e32 v249, v252
	s_nop 0
	v_fma_f32 v250, -v252, v249, 1.0
	v_fmac_f32_e32 v249, v250, v249
	v_div_scale_f32 v250, vcc, 1.0, v251, 1.0
	v_mul_f32_e32 v253, v250, v249
	v_fma_f32 v213, -v252, v253, v250
	v_fmac_f32_e32 v253, v213, v249
	v_fma_f32 v252, -v252, v253, v250
	v_div_fmas_f32 v252, v252, v249, v253
	v_div_fixup_f32 v253, v252, v251, 1.0
	v_mul_f32_e32 v240, v240, v253
	v_mul_f32_e32 v241, v241, v253
	v_mul_f32_e32 v242, v242, v253
	v_mul_f32_e32 v243, v243, v253
	v_mul_f32_e32 v245, v245, v253
	v_mul_f32_e32 v246, v246, v253
	v_mul_f32_e32 v247, v247, v253
	v_mul_f32_e32 v248, v248, v253
	v_mul_f32_e32 v240, v224, v240
	v_mul_f32_e32 v241, v225, v241
	v_mul_f32_e32 v242, v226, v242
	v_mul_f32_e32 v243, v227, v243
	v_mul_f32_e32 v245, v228, v245
	v_mul_f32_e32 v246, v229, v246
	v_mul_f32_e32 v247, v230, v247
	v_mul_f32_e32 v248, v231, v248
	v_add_u32_e32 v249, 0x1000, v212
	v_mov_b32_dpp v232, v240 quad_perm:[1,0,3,2] row_mask:0xf bank_mask:0xf bound_ctrl:1
	v_mov_b32_dpp v233, v241 quad_perm:[1,0,3,2] row_mask:0xf bank_mask:0xf bound_ctrl:1
	v_mov_b32_dpp v234, v242 quad_perm:[1,0,3,2] row_mask:0xf bank_mask:0xf bound_ctrl:1
	v_mov_b32_dpp v235, v243 quad_perm:[1,0,3,2] row_mask:0xf bank_mask:0xf bound_ctrl:1
	v_mov_b32_dpp v2, v245 quad_perm:[1,0,3,2] row_mask:0xf bank_mask:0xf bound_ctrl:1
	v_mov_b32_dpp v3, v246 quad_perm:[1,0,3,2] row_mask:0xf bank_mask:0xf bound_ctrl:1
	v_mov_b32_dpp v5, v247 quad_perm:[1,0,3,2] row_mask:0xf bank_mask:0xf bound_ctrl:1
	v_mov_b32_dpp v151, v248 quad_perm:[1,0,3,2] row_mask:0xf bank_mask:0xf bound_ctrl:1
	v_cvt_pk_bf16_f32 v232, v240, v232
	v_cvt_pk_bf16_f32 v233, v233, v241
	v_cndmask_b32_e64 v232, v233, v232, s[60:61]
	global_store_dword v249, v232, s[58:59] offset:0
	v_cvt_pk_bf16_f32 v234, v242, v234
	v_cvt_pk_bf16_f32 v235, v235, v243
	v_cndmask_b32_e64 v234, v235, v234, s[60:61]
	global_store_dword v249, v234, s[58:59] offset:128
	v_cvt_pk_bf16_f32 v2, v245, v2
	v_cvt_pk_bf16_f32 v3, v3, v246
	v_cndmask_b32_e64 v2, v3, v2, s[60:61]
	global_store_dword v249, v2, s[58:59] offset:256
	v_cvt_pk_bf16_f32 v5, v247, v5
	v_cvt_pk_bf16_f32 v151, v151, v248
	v_cndmask_b32_e64 v5, v151, v5, s[60:61]
	global_store_dword v249, v5, s[58:59] offset:384
	s_waitcnt vmcnt(21)
	v_lshlrev_b32_e32 v250, 16, v160
	v_mul_f32_e32 v249, v132, v149
	v_fma_f32 v240, -v17, v249, v250
	v_and_b32_e32 v250, 0xffff0000, v160
	v_mul_f32_e32 v249, v116, v149
	v_fma_f32 v241, -v17, v249, v250
	v_lshlrev_b32_e32 v250, 16, v161
	v_mul_f32_e32 v249, v100, v149
	v_fma_f32 v242, -v17, v249, v250
	v_and_b32_e32 v250, 0xffff0000, v161
	v_mul_f32_e32 v249, v84, v149
	v_fma_f32 v243, -v17, v249, v250
	v_lshlrev_b32_e32 v250, 16, v162
	v_mul_f32_e32 v249, v68, v149
	v_fma_f32 v245, -v17, v249, v250
	v_and_b32_e32 v250, 0xffff0000, v162
	v_mul_f32_e32 v249, v52, v149
	v_fma_f32 v246, -v17, v249, v250
	v_lshlrev_b32_e32 v250, 16, v163
	v_mul_f32_e32 v249, v36, v149
	v_fma_f32 v247, -v17, v249, v250
	v_and_b32_e32 v250, 0xffff0000, v163
	v_mul_f32_e32 v249, v20, v149
	v_fma_f32 v248, -v17, v249, v250
	v_mul_f32_e32 v251, v241, v241
	v_fmac_f32_e32 v251, v240, v240
	v_fmac_f32_e32 v251, v242, v242
	v_fmac_f32_e32 v251, v243, v243
	v_fmac_f32_e32 v251, v245, v245
	v_fmac_f32_e32 v251, v246, v246
	v_fmac_f32_e32 v251, v247, v247
	v_fmac_f32_e32 v251, v248, v248
	s_nop 1
	v_add_f32_dpp v251, v251, v251 quad_perm:[1,0,3,2] row_mask:0xf bank_mask:0xf bound_ctrl:1
	s_nop 1
	v_add_f32_dpp v251, v251, v251 quad_perm:[2,3,0,1] row_mask:0xf bank_mask:0xf bound_ctrl:1
	s_nop 1
	v_add_f32_dpp v251, v251, v251 row_half_mirror row_mask:0xf bank_mask:0xf bound_ctrl:1
	s_nop 1
	v_add_f32_dpp v251, v251, v251 row_mirror row_mask:0xf bank_mask:0xf bound_ctrl:1
	ds_bpermute_b32 v252, v0, v251
	s_waitcnt lgkmcnt(0)
	v_add_f32_e32 v251, v251, v252
	v_fmamk_f32 v251, v251, 0x3b800000, v238
	v_mul_f32_e32 v252, 0x4f800000, v251
	v_cmp_gt_f32_e32 vcc, s24, v251
	s_nop 1
	v_cndmask_b32_e32 v251, v251, v252, vcc
	v_sqrt_f32_e32 v252, v251
	s_nop 0
	v_add_u32_e32 v249, -1, v252
	v_fma_f32 v250, -v249, v252, v251
	v_cmp_ge_f32_e64 s[6:7], 0, v250
	v_add_u32_e32 v250, 1, v252
	s_nop 0
	v_cndmask_b32_e64 v249, v252, v249, s[6:7]
	v_fma_f32 v252, -v250, v252, v251
	v_cmp_lt_f32_e64 s[6:7], 0, v252
	s_nop 1
	v_cndmask_b32_e64 v252, v249, v250, s[6:7]
	v_mul_f32_e32 v249, 0x37800000, v252
	v_cndmask_b32_e32 v252, v252, v249, vcc
	v_cmp_class_f32_e32 vcc, v251, v239
	s_nop 1
	v_cndmask_b32_e32 v251, v252, v251, vcc
	v_div_scale_f32 v252, s[2:3], v251, v251, 1.0
	v_rcp_f32_e32 v249, v252
	s_nop 0
	v_fma_f32 v250, -v252, v249, 1.0
	v_fmac_f32_e32 v249, v250, v249
	v_div_scale_f32 v250, vcc, 1.0, v251, 1.0
	v_mul_f32_e32 v253, v250, v249
	v_fma_f32 v213, -v252, v253, v250
	v_fmac_f32_e32 v253, v213, v249
	v_fma_f32 v252, -v252, v253, v250
	v_div_fmas_f32 v252, v252, v249, v253
	v_div_fixup_f32 v253, v252, v251, 1.0
	v_mul_f32_e32 v240, v240, v253
	v_mul_f32_e32 v241, v241, v253
	v_mul_f32_e32 v242, v242, v253
	v_mul_f32_e32 v243, v243, v253
	v_mul_f32_e32 v245, v245, v253
	v_mul_f32_e32 v246, v246, v253
	v_mul_f32_e32 v247, v247, v253
	v_mul_f32_e32 v248, v248, v253
	v_mul_f32_e32 v240, v224, v240
	v_mul_f32_e32 v241, v225, v241
	v_mul_f32_e32 v242, v226, v242
	v_mul_f32_e32 v243, v227, v243
	v_mul_f32_e32 v245, v228, v245
	v_mul_f32_e32 v246, v229, v246
	v_mul_f32_e32 v247, v230, v247
	v_mul_f32_e32 v248, v231, v248
	v_add_u32_e32 v249, 0x2000, v212
	v_mov_b32_dpp v232, v240 quad_perm:[1,0,3,2] row_mask:0xf bank_mask:0xf bound_ctrl:1
	v_mov_b32_dpp v233, v241 quad_perm:[1,0,3,2] row_mask:0xf bank_mask:0xf bound_ctrl:1
	v_mov_b32_dpp v234, v242 quad_perm:[1,0,3,2] row_mask:0xf bank_mask:0xf bound_ctrl:1
	v_mov_b32_dpp v235, v243 quad_perm:[1,0,3,2] row_mask:0xf bank_mask:0xf bound_ctrl:1
	v_mov_b32_dpp v2, v245 quad_perm:[1,0,3,2] row_mask:0xf bank_mask:0xf bound_ctrl:1
	v_mov_b32_dpp v3, v246 quad_perm:[1,0,3,2] row_mask:0xf bank_mask:0xf bound_ctrl:1
	v_mov_b32_dpp v5, v247 quad_perm:[1,0,3,2] row_mask:0xf bank_mask:0xf bound_ctrl:1
	v_mov_b32_dpp v151, v248 quad_perm:[1,0,3,2] row_mask:0xf bank_mask:0xf bound_ctrl:1
	v_cvt_pk_bf16_f32 v232, v240, v232
	v_cvt_pk_bf16_f32 v233, v233, v241
	v_cndmask_b32_e64 v232, v233, v232, s[60:61]
	global_store_dword v249, v232, s[58:59] offset:0
	v_cvt_pk_bf16_f32 v234, v242, v234
	v_cvt_pk_bf16_f32 v235, v235, v243
	v_cndmask_b32_e64 v234, v235, v234, s[60:61]
	global_store_dword v249, v234, s[58:59] offset:128
	v_cvt_pk_bf16_f32 v2, v245, v2
	v_cvt_pk_bf16_f32 v3, v3, v246
	v_cndmask_b32_e64 v2, v3, v2, s[60:61]
	global_store_dword v249, v2, s[58:59] offset:256
	v_cvt_pk_bf16_f32 v5, v247, v5
	v_cvt_pk_bf16_f32 v151, v151, v248
	v_cndmask_b32_e64 v5, v151, v5, s[60:61]
	global_store_dword v249, v5, s[58:59] offset:384
	s_waitcnt vmcnt(24)
	v_lshlrev_b32_e32 v250, 16, v164
	v_mul_f32_e32 v249, v133, v148
	v_fma_f32 v240, -v17, v249, v250
	v_and_b32_e32 v250, 0xffff0000, v164
	v_mul_f32_e32 v249, v117, v148
	v_fma_f32 v241, -v17, v249, v250
	v_lshlrev_b32_e32 v250, 16, v165
	v_mul_f32_e32 v249, v101, v148
	v_fma_f32 v242, -v17, v249, v250
	v_and_b32_e32 v250, 0xffff0000, v165
	v_mul_f32_e32 v249, v85, v148
	v_fma_f32 v243, -v17, v249, v250
	v_lshlrev_b32_e32 v250, 16, v166
	v_mul_f32_e32 v249, v69, v148
	v_fma_f32 v245, -v17, v249, v250
	v_and_b32_e32 v250, 0xffff0000, v166
	v_mul_f32_e32 v249, v53, v148
	v_fma_f32 v246, -v17, v249, v250
	v_lshlrev_b32_e32 v250, 16, v167
	v_mul_f32_e32 v249, v37, v148
	v_fma_f32 v247, -v17, v249, v250
	v_and_b32_e32 v250, 0xffff0000, v167
	v_mul_f32_e32 v249, v21, v148
	v_fma_f32 v248, -v17, v249, v250
	v_mul_f32_e32 v251, v241, v241
	v_fmac_f32_e32 v251, v240, v240
	v_fmac_f32_e32 v251, v242, v242
	v_fmac_f32_e32 v251, v243, v243
	v_fmac_f32_e32 v251, v245, v245
	v_fmac_f32_e32 v251, v246, v246
	v_fmac_f32_e32 v251, v247, v247
	v_fmac_f32_e32 v251, v248, v248
	s_nop 1
	v_add_f32_dpp v251, v251, v251 quad_perm:[1,0,3,2] row_mask:0xf bank_mask:0xf bound_ctrl:1
	s_nop 1
	v_add_f32_dpp v251, v251, v251 quad_perm:[2,3,0,1] row_mask:0xf bank_mask:0xf bound_ctrl:1
	s_nop 1
	v_add_f32_dpp v251, v251, v251 row_half_mirror row_mask:0xf bank_mask:0xf bound_ctrl:1
	s_nop 1
	v_add_f32_dpp v251, v251, v251 row_mirror row_mask:0xf bank_mask:0xf bound_ctrl:1
	ds_bpermute_b32 v252, v0, v251
	s_waitcnt lgkmcnt(0)
	v_add_f32_e32 v251, v251, v252
	v_fmamk_f32 v251, v251, 0x3b800000, v238
	v_mul_f32_e32 v252, 0x4f800000, v251
	v_cmp_gt_f32_e32 vcc, s24, v251
	s_nop 1
	v_cndmask_b32_e32 v251, v251, v252, vcc
	v_sqrt_f32_e32 v252, v251
	s_nop 0
	v_add_u32_e32 v249, -1, v252
	v_fma_f32 v250, -v249, v252, v251
	v_cmp_ge_f32_e64 s[6:7], 0, v250
	v_add_u32_e32 v250, 1, v252
	s_nop 0
	v_cndmask_b32_e64 v249, v252, v249, s[6:7]
	v_fma_f32 v252, -v250, v252, v251
	v_cmp_lt_f32_e64 s[6:7], 0, v252
	s_nop 1
	v_cndmask_b32_e64 v252, v249, v250, s[6:7]
	v_mul_f32_e32 v249, 0x37800000, v252
	v_cndmask_b32_e32 v252, v252, v249, vcc
	v_cmp_class_f32_e32 vcc, v251, v239
	s_nop 1
	v_cndmask_b32_e32 v251, v252, v251, vcc
	v_div_scale_f32 v252, s[2:3], v251, v251, 1.0
	v_rcp_f32_e32 v249, v252
	s_nop 0
	v_fma_f32 v250, -v252, v249, 1.0
	v_fmac_f32_e32 v249, v250, v249
	v_div_scale_f32 v250, vcc, 1.0, v251, 1.0
	v_mul_f32_e32 v253, v250, v249
	v_fma_f32 v213, -v252, v253, v250
	v_fmac_f32_e32 v253, v213, v249
	v_fma_f32 v252, -v252, v253, v250
	v_div_fmas_f32 v252, v252, v249, v253
	v_div_fixup_f32 v253, v252, v251, 1.0
	v_mul_f32_e32 v240, v240, v253
	v_mul_f32_e32 v241, v241, v253
	v_mul_f32_e32 v242, v242, v253
	v_mul_f32_e32 v243, v243, v253
	v_mul_f32_e32 v245, v245, v253
	v_mul_f32_e32 v246, v246, v253
	v_mul_f32_e32 v247, v247, v253
	v_mul_f32_e32 v248, v248, v253
	v_mul_f32_e32 v240, v224, v240
	v_mul_f32_e32 v241, v225, v241
	v_mul_f32_e32 v242, v226, v242
	v_mul_f32_e32 v243, v227, v243
	v_mul_f32_e32 v245, v228, v245
	v_mul_f32_e32 v246, v229, v246
	v_mul_f32_e32 v247, v230, v247
	v_mul_f32_e32 v248, v231, v248
	v_add_u32_e32 v249, 0x3000, v212
	v_mov_b32_dpp v232, v240 quad_perm:[1,0,3,2] row_mask:0xf bank_mask:0xf bound_ctrl:1
	v_mov_b32_dpp v233, v241 quad_perm:[1,0,3,2] row_mask:0xf bank_mask:0xf bound_ctrl:1
	v_mov_b32_dpp v234, v242 quad_perm:[1,0,3,2] row_mask:0xf bank_mask:0xf bound_ctrl:1
	v_mov_b32_dpp v235, v243 quad_perm:[1,0,3,2] row_mask:0xf bank_mask:0xf bound_ctrl:1
	v_mov_b32_dpp v2, v245 quad_perm:[1,0,3,2] row_mask:0xf bank_mask:0xf bound_ctrl:1
	v_mov_b32_dpp v3, v246 quad_perm:[1,0,3,2] row_mask:0xf bank_mask:0xf bound_ctrl:1
	v_mov_b32_dpp v5, v247 quad_perm:[1,0,3,2] row_mask:0xf bank_mask:0xf bound_ctrl:1
	v_mov_b32_dpp v151, v248 quad_perm:[1,0,3,2] row_mask:0xf bank_mask:0xf bound_ctrl:1
	v_cvt_pk_bf16_f32 v232, v240, v232
	v_cvt_pk_bf16_f32 v233, v233, v241
	v_cndmask_b32_e64 v232, v233, v232, s[60:61]
	global_store_dword v249, v232, s[58:59] offset:0
	v_cvt_pk_bf16_f32 v234, v242, v234
	v_cvt_pk_bf16_f32 v235, v235, v243
	v_cndmask_b32_e64 v234, v235, v234, s[60:61]
	global_store_dword v249, v234, s[58:59] offset:128
	v_cvt_pk_bf16_f32 v2, v245, v2
	v_cvt_pk_bf16_f32 v3, v3, v246
	v_cndmask_b32_e64 v2, v3, v2, s[60:61]
	global_store_dword v249, v2, s[58:59] offset:256
	v_cvt_pk_bf16_f32 v5, v247, v5
	v_cvt_pk_bf16_f32 v151, v151, v248
	v_cndmask_b32_e64 v5, v151, v5, s[60:61]
	global_store_dword v249, v5, s[58:59] offset:384
	s_waitcnt vmcnt(27)
	v_lshlrev_b32_e32 v250, 16, v168
	v_mul_f32_e32 v249, v134, v147
	v_fma_f32 v240, -v17, v249, v250
	v_and_b32_e32 v250, 0xffff0000, v168
	v_mul_f32_e32 v249, v118, v147
	v_fma_f32 v241, -v17, v249, v250
	v_lshlrev_b32_e32 v250, 16, v169
	v_mul_f32_e32 v249, v102, v147
	v_fma_f32 v242, -v17, v249, v250
	v_and_b32_e32 v250, 0xffff0000, v169
	v_mul_f32_e32 v249, v86, v147
	v_fma_f32 v243, -v17, v249, v250
	v_lshlrev_b32_e32 v250, 16, v170
	v_mul_f32_e32 v249, v70, v147
	v_fma_f32 v245, -v17, v249, v250
	v_and_b32_e32 v250, 0xffff0000, v170
	v_mul_f32_e32 v249, v54, v147
	v_fma_f32 v246, -v17, v249, v250
	v_lshlrev_b32_e32 v250, 16, v171
	v_mul_f32_e32 v249, v38, v147
	v_fma_f32 v247, -v17, v249, v250
	v_and_b32_e32 v250, 0xffff0000, v171
	v_mul_f32_e32 v249, v22, v147
	v_fma_f32 v248, -v17, v249, v250
	v_mul_f32_e32 v251, v241, v241
	v_fmac_f32_e32 v251, v240, v240
	v_fmac_f32_e32 v251, v242, v242
	v_fmac_f32_e32 v251, v243, v243
	v_fmac_f32_e32 v251, v245, v245
	v_fmac_f32_e32 v251, v246, v246
	v_fmac_f32_e32 v251, v247, v247
	v_fmac_f32_e32 v251, v248, v248
	s_nop 1
	v_add_f32_dpp v251, v251, v251 quad_perm:[1,0,3,2] row_mask:0xf bank_mask:0xf bound_ctrl:1
	s_nop 1
	v_add_f32_dpp v251, v251, v251 quad_perm:[2,3,0,1] row_mask:0xf bank_mask:0xf bound_ctrl:1
	s_nop 1
	v_add_f32_dpp v251, v251, v251 row_half_mirror row_mask:0xf bank_mask:0xf bound_ctrl:1
	s_nop 1
	v_add_f32_dpp v251, v251, v251 row_mirror row_mask:0xf bank_mask:0xf bound_ctrl:1
	ds_bpermute_b32 v252, v0, v251
	s_waitcnt lgkmcnt(0)
	v_add_f32_e32 v251, v251, v252
	v_fmamk_f32 v251, v251, 0x3b800000, v238
	v_mul_f32_e32 v252, 0x4f800000, v251
	v_cmp_gt_f32_e32 vcc, s24, v251
	s_nop 1
	v_cndmask_b32_e32 v251, v251, v252, vcc
	v_sqrt_f32_e32 v252, v251
	s_nop 0
	v_add_u32_e32 v249, -1, v252
	v_fma_f32 v250, -v249, v252, v251
	v_cmp_ge_f32_e64 s[6:7], 0, v250
	v_add_u32_e32 v250, 1, v252
	s_nop 0
	v_cndmask_b32_e64 v249, v252, v249, s[6:7]
	v_fma_f32 v252, -v250, v252, v251
	v_cmp_lt_f32_e64 s[6:7], 0, v252
	s_nop 1
	v_cndmask_b32_e64 v252, v249, v250, s[6:7]
	v_mul_f32_e32 v249, 0x37800000, v252
	v_cndmask_b32_e32 v252, v252, v249, vcc
	v_cmp_class_f32_e32 vcc, v251, v239
	s_nop 1
	v_cndmask_b32_e32 v251, v252, v251, vcc
	v_div_scale_f32 v252, s[2:3], v251, v251, 1.0
	v_rcp_f32_e32 v249, v252
	s_nop 0
	v_fma_f32 v250, -v252, v249, 1.0
	v_fmac_f32_e32 v249, v250, v249
	v_div_scale_f32 v250, vcc, 1.0, v251, 1.0
	v_mul_f32_e32 v253, v250, v249
	v_fma_f32 v213, -v252, v253, v250
	v_fmac_f32_e32 v253, v213, v249
	v_fma_f32 v252, -v252, v253, v250
	v_div_fmas_f32 v252, v252, v249, v253
	v_div_fixup_f32 v253, v252, v251, 1.0
	v_mul_f32_e32 v240, v240, v253
	v_mul_f32_e32 v241, v241, v253
	v_mul_f32_e32 v242, v242, v253
	v_mul_f32_e32 v243, v243, v253
	v_mul_f32_e32 v245, v245, v253
	v_mul_f32_e32 v246, v246, v253
	v_mul_f32_e32 v247, v247, v253
	v_mul_f32_e32 v248, v248, v253
	v_mul_f32_e32 v240, v224, v240
	v_mul_f32_e32 v241, v225, v241
	v_mul_f32_e32 v242, v226, v242
	v_mul_f32_e32 v243, v227, v243
	v_mul_f32_e32 v245, v228, v245
	v_mul_f32_e32 v246, v229, v246
	v_mul_f32_e32 v247, v230, v247
	v_mul_f32_e32 v248, v231, v248
	v_add_u32_e32 v249, 0x8000, v212
	v_mov_b32_dpp v232, v240 quad_perm:[1,0,3,2] row_mask:0xf bank_mask:0xf bound_ctrl:1
	v_mov_b32_dpp v233, v241 quad_perm:[1,0,3,2] row_mask:0xf bank_mask:0xf bound_ctrl:1
	v_mov_b32_dpp v234, v242 quad_perm:[1,0,3,2] row_mask:0xf bank_mask:0xf bound_ctrl:1
	v_mov_b32_dpp v235, v243 quad_perm:[1,0,3,2] row_mask:0xf bank_mask:0xf bound_ctrl:1
	v_mov_b32_dpp v2, v245 quad_perm:[1,0,3,2] row_mask:0xf bank_mask:0xf bound_ctrl:1
	v_mov_b32_dpp v3, v246 quad_perm:[1,0,3,2] row_mask:0xf bank_mask:0xf bound_ctrl:1
	v_mov_b32_dpp v5, v247 quad_perm:[1,0,3,2] row_mask:0xf bank_mask:0xf bound_ctrl:1
	v_mov_b32_dpp v151, v248 quad_perm:[1,0,3,2] row_mask:0xf bank_mask:0xf bound_ctrl:1
	v_cvt_pk_bf16_f32 v232, v240, v232
	v_cvt_pk_bf16_f32 v233, v233, v241
	v_cndmask_b32_e64 v232, v233, v232, s[60:61]
	global_store_dword v249, v232, s[58:59] offset:0
	v_cvt_pk_bf16_f32 v234, v242, v234
	v_cvt_pk_bf16_f32 v235, v235, v243
	v_cndmask_b32_e64 v234, v235, v234, s[60:61]
	global_store_dword v249, v234, s[58:59] offset:128
	v_cvt_pk_bf16_f32 v2, v245, v2
	v_cvt_pk_bf16_f32 v3, v3, v246
	v_cndmask_b32_e64 v2, v3, v2, s[60:61]
	global_store_dword v249, v2, s[58:59] offset:256
	v_cvt_pk_bf16_f32 v5, v247, v5
	v_cvt_pk_bf16_f32 v151, v151, v248
	v_cndmask_b32_e64 v5, v151, v5, s[60:61]
	global_store_dword v249, v5, s[58:59] offset:384
	s_waitcnt vmcnt(30)
	v_lshlrev_b32_e32 v250, 16, v172
	v_mul_f32_e32 v249, v135, v146
	v_fma_f32 v240, -v17, v249, v250
	v_and_b32_e32 v250, 0xffff0000, v172
	v_mul_f32_e32 v249, v119, v146
	v_fma_f32 v241, -v17, v249, v250
	v_lshlrev_b32_e32 v250, 16, v173
	v_mul_f32_e32 v249, v103, v146
	v_fma_f32 v242, -v17, v249, v250
	v_and_b32_e32 v250, 0xffff0000, v173
	v_mul_f32_e32 v249, v87, v146
	v_fma_f32 v243, -v17, v249, v250
	v_lshlrev_b32_e32 v250, 16, v174
	v_mul_f32_e32 v249, v71, v146
	v_fma_f32 v245, -v17, v249, v250
	v_and_b32_e32 v250, 0xffff0000, v174
	v_mul_f32_e32 v249, v55, v146
	v_fma_f32 v246, -v17, v249, v250
	v_lshlrev_b32_e32 v250, 16, v175
	v_mul_f32_e32 v249, v39, v146
	v_fma_f32 v247, -v17, v249, v250
	v_and_b32_e32 v250, 0xffff0000, v175
	v_mul_f32_e32 v249, v23, v146
	v_fma_f32 v248, -v17, v249, v250
	v_mul_f32_e32 v251, v241, v241
	v_fmac_f32_e32 v251, v240, v240
	v_fmac_f32_e32 v251, v242, v242
	v_fmac_f32_e32 v251, v243, v243
	v_fmac_f32_e32 v251, v245, v245
	v_fmac_f32_e32 v251, v246, v246
	v_fmac_f32_e32 v251, v247, v247
	v_fmac_f32_e32 v251, v248, v248
	s_nop 1
	v_add_f32_dpp v251, v251, v251 quad_perm:[1,0,3,2] row_mask:0xf bank_mask:0xf bound_ctrl:1
	s_nop 1
	v_add_f32_dpp v251, v251, v251 quad_perm:[2,3,0,1] row_mask:0xf bank_mask:0xf bound_ctrl:1
	s_nop 1
	v_add_f32_dpp v251, v251, v251 row_half_mirror row_mask:0xf bank_mask:0xf bound_ctrl:1
	s_nop 1
	v_add_f32_dpp v251, v251, v251 row_mirror row_mask:0xf bank_mask:0xf bound_ctrl:1
	ds_bpermute_b32 v252, v0, v251
	s_waitcnt lgkmcnt(0)
	v_add_f32_e32 v251, v251, v252
	v_fmamk_f32 v251, v251, 0x3b800000, v238
	v_mul_f32_e32 v252, 0x4f800000, v251
	v_cmp_gt_f32_e32 vcc, s24, v251
	s_nop 1
	v_cndmask_b32_e32 v251, v251, v252, vcc
	v_sqrt_f32_e32 v252, v251
	s_nop 0
	v_add_u32_e32 v249, -1, v252
	v_fma_f32 v250, -v249, v252, v251
	v_cmp_ge_f32_e64 s[6:7], 0, v250
	v_add_u32_e32 v250, 1, v252
	s_nop 0
	v_cndmask_b32_e64 v249, v252, v249, s[6:7]
	v_fma_f32 v252, -v250, v252, v251
	v_cmp_lt_f32_e64 s[6:7], 0, v252
	s_nop 1
	v_cndmask_b32_e64 v252, v249, v250, s[6:7]
	v_mul_f32_e32 v249, 0x37800000, v252
	v_cndmask_b32_e32 v252, v252, v249, vcc
	v_cmp_class_f32_e32 vcc, v251, v239
	s_nop 1
	v_cndmask_b32_e32 v251, v252, v251, vcc
	v_div_scale_f32 v252, s[2:3], v251, v251, 1.0
	v_rcp_f32_e32 v249, v252
	s_nop 0
	v_fma_f32 v250, -v252, v249, 1.0
	v_fmac_f32_e32 v249, v250, v249
	v_div_scale_f32 v250, vcc, 1.0, v251, 1.0
	v_mul_f32_e32 v253, v250, v249
	v_fma_f32 v213, -v252, v253, v250
	v_fmac_f32_e32 v253, v213, v249
	v_fma_f32 v252, -v252, v253, v250
	v_div_fmas_f32 v252, v252, v249, v253
	v_div_fixup_f32 v253, v252, v251, 1.0
	v_mul_f32_e32 v240, v240, v253
	v_mul_f32_e32 v241, v241, v253
	v_mul_f32_e32 v242, v242, v253
	v_mul_f32_e32 v243, v243, v253
	v_mul_f32_e32 v245, v245, v253
	v_mul_f32_e32 v246, v246, v253
	v_mul_f32_e32 v247, v247, v253
	v_mul_f32_e32 v248, v248, v253
	v_mul_f32_e32 v240, v224, v240
	v_mul_f32_e32 v241, v225, v241
	v_mul_f32_e32 v242, v226, v242
	v_mul_f32_e32 v243, v227, v243
	v_mul_f32_e32 v245, v228, v245
	v_mul_f32_e32 v246, v229, v246
	v_mul_f32_e32 v247, v230, v247
	v_mul_f32_e32 v248, v231, v248
	v_add_u32_e32 v249, 0x9000, v212
	v_mov_b32_dpp v232, v240 quad_perm:[1,0,3,2] row_mask:0xf bank_mask:0xf bound_ctrl:1
	v_mov_b32_dpp v233, v241 quad_perm:[1,0,3,2] row_mask:0xf bank_mask:0xf bound_ctrl:1
	v_mov_b32_dpp v234, v242 quad_perm:[1,0,3,2] row_mask:0xf bank_mask:0xf bound_ctrl:1
	v_mov_b32_dpp v235, v243 quad_perm:[1,0,3,2] row_mask:0xf bank_mask:0xf bound_ctrl:1
	v_mov_b32_dpp v2, v245 quad_perm:[1,0,3,2] row_mask:0xf bank_mask:0xf bound_ctrl:1
	v_mov_b32_dpp v3, v246 quad_perm:[1,0,3,2] row_mask:0xf bank_mask:0xf bound_ctrl:1
	v_mov_b32_dpp v5, v247 quad_perm:[1,0,3,2] row_mask:0xf bank_mask:0xf bound_ctrl:1
	v_mov_b32_dpp v151, v248 quad_perm:[1,0,3,2] row_mask:0xf bank_mask:0xf bound_ctrl:1
	v_cvt_pk_bf16_f32 v232, v240, v232
	v_cvt_pk_bf16_f32 v233, v233, v241
	v_cndmask_b32_e64 v232, v233, v232, s[60:61]
	global_store_dword v249, v232, s[58:59] offset:0
	v_cvt_pk_bf16_f32 v234, v242, v234
	v_cvt_pk_bf16_f32 v235, v235, v243
	v_cndmask_b32_e64 v234, v235, v234, s[60:61]
	global_store_dword v249, v234, s[58:59] offset:128
	v_cvt_pk_bf16_f32 v2, v245, v2
	v_cvt_pk_bf16_f32 v3, v3, v246
	v_cndmask_b32_e64 v2, v3, v2, s[60:61]
	global_store_dword v249, v2, s[58:59] offset:256
	v_cvt_pk_bf16_f32 v5, v247, v5
	v_cvt_pk_bf16_f32 v151, v151, v248
	v_cndmask_b32_e64 v5, v151, v5, s[60:61]
	global_store_dword v249, v5, s[58:59] offset:384
	s_waitcnt vmcnt(33)
	v_lshlrev_b32_e32 v250, 16, v176
	v_mul_f32_e32 v249, v136, v15
	v_fma_f32 v240, -v17, v249, v250
	v_and_b32_e32 v250, 0xffff0000, v176
	v_mul_f32_e32 v249, v120, v15
	v_fma_f32 v241, -v17, v249, v250
	v_lshlrev_b32_e32 v250, 16, v177
	v_mul_f32_e32 v249, v104, v15
	v_fma_f32 v242, -v17, v249, v250
	v_and_b32_e32 v250, 0xffff0000, v177
	v_mul_f32_e32 v249, v88, v15
	v_fma_f32 v243, -v17, v249, v250
	v_lshlrev_b32_e32 v250, 16, v178
	v_mul_f32_e32 v249, v72, v15
	v_fma_f32 v245, -v17, v249, v250
	v_and_b32_e32 v250, 0xffff0000, v178
	v_mul_f32_e32 v249, v56, v15
	v_fma_f32 v246, -v17, v249, v250
	v_lshlrev_b32_e32 v250, 16, v179
	v_mul_f32_e32 v249, v40, v15
	v_fma_f32 v247, -v17, v249, v250
	v_and_b32_e32 v250, 0xffff0000, v179
	v_mul_f32_e32 v249, v24, v15
	v_fma_f32 v248, -v17, v249, v250
	v_mul_f32_e32 v251, v241, v241
	v_fmac_f32_e32 v251, v240, v240
	v_fmac_f32_e32 v251, v242, v242
	v_fmac_f32_e32 v251, v243, v243
	v_fmac_f32_e32 v251, v245, v245
	v_fmac_f32_e32 v251, v246, v246
	v_fmac_f32_e32 v251, v247, v247
	v_fmac_f32_e32 v251, v248, v248
	s_nop 1
	v_add_f32_dpp v251, v251, v251 quad_perm:[1,0,3,2] row_mask:0xf bank_mask:0xf bound_ctrl:1
	s_nop 1
	v_add_f32_dpp v251, v251, v251 quad_perm:[2,3,0,1] row_mask:0xf bank_mask:0xf bound_ctrl:1
	s_nop 1
	v_add_f32_dpp v251, v251, v251 row_half_mirror row_mask:0xf bank_mask:0xf bound_ctrl:1
	s_nop 1
	v_add_f32_dpp v251, v251, v251 row_mirror row_mask:0xf bank_mask:0xf bound_ctrl:1
	ds_bpermute_b32 v252, v0, v251
	s_waitcnt lgkmcnt(0)
	v_add_f32_e32 v251, v251, v252
	v_fmamk_f32 v251, v251, 0x3b800000, v238
	v_mul_f32_e32 v252, 0x4f800000, v251
	v_cmp_gt_f32_e32 vcc, s24, v251
	s_nop 1
	v_cndmask_b32_e32 v251, v251, v252, vcc
	v_sqrt_f32_e32 v252, v251
	s_nop 0
	v_add_u32_e32 v249, -1, v252
	v_fma_f32 v250, -v249, v252, v251
	v_cmp_ge_f32_e64 s[6:7], 0, v250
	v_add_u32_e32 v250, 1, v252
	s_nop 0
	v_cndmask_b32_e64 v249, v252, v249, s[6:7]
	v_fma_f32 v252, -v250, v252, v251
	v_cmp_lt_f32_e64 s[6:7], 0, v252
	s_nop 1
	v_cndmask_b32_e64 v252, v249, v250, s[6:7]
	v_mul_f32_e32 v249, 0x37800000, v252
	v_cndmask_b32_e32 v252, v252, v249, vcc
	v_cmp_class_f32_e32 vcc, v251, v239
	s_nop 1
	v_cndmask_b32_e32 v251, v252, v251, vcc
	v_div_scale_f32 v252, s[2:3], v251, v251, 1.0
	v_rcp_f32_e32 v249, v252
	s_nop 0
	v_fma_f32 v250, -v252, v249, 1.0
	v_fmac_f32_e32 v249, v250, v249
	v_div_scale_f32 v250, vcc, 1.0, v251, 1.0
	v_mul_f32_e32 v253, v250, v249
	v_fma_f32 v213, -v252, v253, v250
	v_fmac_f32_e32 v253, v213, v249
	v_fma_f32 v252, -v252, v253, v250
	v_div_fmas_f32 v252, v252, v249, v253
	v_div_fixup_f32 v253, v252, v251, 1.0
	v_mul_f32_e32 v240, v240, v253
	v_mul_f32_e32 v241, v241, v253
	v_mul_f32_e32 v242, v242, v253
	v_mul_f32_e32 v243, v243, v253
	v_mul_f32_e32 v245, v245, v253
	v_mul_f32_e32 v246, v246, v253
	v_mul_f32_e32 v247, v247, v253
	v_mul_f32_e32 v248, v248, v253
	v_mul_f32_e32 v240, v224, v240
	v_mul_f32_e32 v241, v225, v241
	v_mul_f32_e32 v242, v226, v242
	v_mul_f32_e32 v243, v227, v243
	v_mul_f32_e32 v245, v228, v245
	v_mul_f32_e32 v246, v229, v246
	v_mul_f32_e32 v247, v230, v247
	v_mul_f32_e32 v248, v231, v248
	v_add_u32_e32 v249, 0xa000, v212
	v_mov_b32_dpp v232, v240 quad_perm:[1,0,3,2] row_mask:0xf bank_mask:0xf bound_ctrl:1
	v_mov_b32_dpp v233, v241 quad_perm:[1,0,3,2] row_mask:0xf bank_mask:0xf bound_ctrl:1
	v_mov_b32_dpp v234, v242 quad_perm:[1,0,3,2] row_mask:0xf bank_mask:0xf bound_ctrl:1
	v_mov_b32_dpp v235, v243 quad_perm:[1,0,3,2] row_mask:0xf bank_mask:0xf bound_ctrl:1
	v_mov_b32_dpp v2, v245 quad_perm:[1,0,3,2] row_mask:0xf bank_mask:0xf bound_ctrl:1
	v_mov_b32_dpp v3, v246 quad_perm:[1,0,3,2] row_mask:0xf bank_mask:0xf bound_ctrl:1
	v_mov_b32_dpp v5, v247 quad_perm:[1,0,3,2] row_mask:0xf bank_mask:0xf bound_ctrl:1
	v_mov_b32_dpp v151, v248 quad_perm:[1,0,3,2] row_mask:0xf bank_mask:0xf bound_ctrl:1
	v_cvt_pk_bf16_f32 v232, v240, v232
	v_cvt_pk_bf16_f32 v233, v233, v241
	v_cndmask_b32_e64 v232, v233, v232, s[60:61]
	global_store_dword v249, v232, s[58:59] offset:0
	v_cvt_pk_bf16_f32 v234, v242, v234
	v_cvt_pk_bf16_f32 v235, v235, v243
	v_cndmask_b32_e64 v234, v235, v234, s[60:61]
	global_store_dword v249, v234, s[58:59] offset:128
	v_cvt_pk_bf16_f32 v2, v245, v2
	v_cvt_pk_bf16_f32 v3, v3, v246
	v_cndmask_b32_e64 v2, v3, v2, s[60:61]
	global_store_dword v249, v2, s[58:59] offset:256
	v_cvt_pk_bf16_f32 v5, v247, v5
	v_cvt_pk_bf16_f32 v151, v151, v248
	v_cndmask_b32_e64 v5, v151, v5, s[60:61]
	global_store_dword v249, v5, s[58:59] offset:384
	s_waitcnt vmcnt(36)
	v_lshlrev_b32_e32 v250, 16, v180
	v_mul_f32_e32 v249, v137, v14
	v_fma_f32 v240, -v17, v249, v250
	v_and_b32_e32 v250, 0xffff0000, v180
	v_mul_f32_e32 v249, v121, v14
	v_fma_f32 v241, -v17, v249, v250
	v_lshlrev_b32_e32 v250, 16, v181
	v_mul_f32_e32 v249, v105, v14
	v_fma_f32 v242, -v17, v249, v250
	v_and_b32_e32 v250, 0xffff0000, v181
	v_mul_f32_e32 v249, v89, v14
	v_fma_f32 v243, -v17, v249, v250
	v_lshlrev_b32_e32 v250, 16, v182
	v_mul_f32_e32 v249, v73, v14
	v_fma_f32 v245, -v17, v249, v250
	v_and_b32_e32 v250, 0xffff0000, v182
	v_mul_f32_e32 v249, v57, v14
	v_fma_f32 v246, -v17, v249, v250
	v_lshlrev_b32_e32 v250, 16, v183
	v_mul_f32_e32 v249, v41, v14
	v_fma_f32 v247, -v17, v249, v250
	v_and_b32_e32 v250, 0xffff0000, v183
	v_mul_f32_e32 v249, v25, v14
	v_fma_f32 v248, -v17, v249, v250
	v_mul_f32_e32 v251, v241, v241
	v_fmac_f32_e32 v251, v240, v240
	v_fmac_f32_e32 v251, v242, v242
	v_fmac_f32_e32 v251, v243, v243
	v_fmac_f32_e32 v251, v245, v245
	v_fmac_f32_e32 v251, v246, v246
	v_fmac_f32_e32 v251, v247, v247
	v_fmac_f32_e32 v251, v248, v248
	s_nop 1
	v_add_f32_dpp v251, v251, v251 quad_perm:[1,0,3,2] row_mask:0xf bank_mask:0xf bound_ctrl:1
	s_nop 1
	v_add_f32_dpp v251, v251, v251 quad_perm:[2,3,0,1] row_mask:0xf bank_mask:0xf bound_ctrl:1
	s_nop 1
	v_add_f32_dpp v251, v251, v251 row_half_mirror row_mask:0xf bank_mask:0xf bound_ctrl:1
	s_nop 1
	v_add_f32_dpp v251, v251, v251 row_mirror row_mask:0xf bank_mask:0xf bound_ctrl:1
	ds_bpermute_b32 v252, v0, v251
	s_waitcnt lgkmcnt(0)
	v_add_f32_e32 v251, v251, v252
	v_fmamk_f32 v251, v251, 0x3b800000, v238
	v_mul_f32_e32 v252, 0x4f800000, v251
	v_cmp_gt_f32_e32 vcc, s24, v251
	s_nop 1
	v_cndmask_b32_e32 v251, v251, v252, vcc
	v_sqrt_f32_e32 v252, v251
	s_nop 0
	v_add_u32_e32 v249, -1, v252
	v_fma_f32 v250, -v249, v252, v251
	v_cmp_ge_f32_e64 s[6:7], 0, v250
	v_add_u32_e32 v250, 1, v252
	s_nop 0
	v_cndmask_b32_e64 v249, v252, v249, s[6:7]
	v_fma_f32 v252, -v250, v252, v251
	v_cmp_lt_f32_e64 s[6:7], 0, v252
	s_nop 1
	v_cndmask_b32_e64 v252, v249, v250, s[6:7]
	v_mul_f32_e32 v249, 0x37800000, v252
	v_cndmask_b32_e32 v252, v252, v249, vcc
	v_cmp_class_f32_e32 vcc, v251, v239
	s_nop 1
	v_cndmask_b32_e32 v251, v252, v251, vcc
	v_div_scale_f32 v252, s[2:3], v251, v251, 1.0
	v_rcp_f32_e32 v249, v252
	s_nop 0
	v_fma_f32 v250, -v252, v249, 1.0
	v_fmac_f32_e32 v249, v250, v249
	v_div_scale_f32 v250, vcc, 1.0, v251, 1.0
	v_mul_f32_e32 v253, v250, v249
	v_fma_f32 v213, -v252, v253, v250
	v_fmac_f32_e32 v253, v213, v249
	v_fma_f32 v252, -v252, v253, v250
	v_div_fmas_f32 v252, v252, v249, v253
	v_div_fixup_f32 v253, v252, v251, 1.0
	v_mul_f32_e32 v240, v240, v253
	v_mul_f32_e32 v241, v241, v253
	v_mul_f32_e32 v242, v242, v253
	v_mul_f32_e32 v243, v243, v253
	v_mul_f32_e32 v245, v245, v253
	v_mul_f32_e32 v246, v246, v253
	v_mul_f32_e32 v247, v247, v253
	v_mul_f32_e32 v248, v248, v253
	v_mul_f32_e32 v240, v224, v240
	v_mul_f32_e32 v241, v225, v241
	v_mul_f32_e32 v242, v226, v242
	v_mul_f32_e32 v243, v227, v243
	v_mul_f32_e32 v245, v228, v245
	v_mul_f32_e32 v246, v229, v246
	v_mul_f32_e32 v247, v230, v247
	v_mul_f32_e32 v248, v231, v248
	v_add_u32_e32 v249, 0xb000, v212
	v_mov_b32_dpp v232, v240 quad_perm:[1,0,3,2] row_mask:0xf bank_mask:0xf bound_ctrl:1
	v_mov_b32_dpp v233, v241 quad_perm:[1,0,3,2] row_mask:0xf bank_mask:0xf bound_ctrl:1
	v_mov_b32_dpp v234, v242 quad_perm:[1,0,3,2] row_mask:0xf bank_mask:0xf bound_ctrl:1
	v_mov_b32_dpp v235, v243 quad_perm:[1,0,3,2] row_mask:0xf bank_mask:0xf bound_ctrl:1
	v_mov_b32_dpp v2, v245 quad_perm:[1,0,3,2] row_mask:0xf bank_mask:0xf bound_ctrl:1
	v_mov_b32_dpp v3, v246 quad_perm:[1,0,3,2] row_mask:0xf bank_mask:0xf bound_ctrl:1
	v_mov_b32_dpp v5, v247 quad_perm:[1,0,3,2] row_mask:0xf bank_mask:0xf bound_ctrl:1
	v_mov_b32_dpp v151, v248 quad_perm:[1,0,3,2] row_mask:0xf bank_mask:0xf bound_ctrl:1
	v_cvt_pk_bf16_f32 v232, v240, v232
	v_cvt_pk_bf16_f32 v233, v233, v241
	v_cndmask_b32_e64 v232, v233, v232, s[60:61]
	global_store_dword v249, v232, s[58:59] offset:0
	v_cvt_pk_bf16_f32 v234, v242, v234
	v_cvt_pk_bf16_f32 v235, v235, v243
	v_cndmask_b32_e64 v234, v235, v234, s[60:61]
	global_store_dword v249, v234, s[58:59] offset:128
	v_cvt_pk_bf16_f32 v2, v245, v2
	v_cvt_pk_bf16_f32 v3, v3, v246
	v_cndmask_b32_e64 v2, v3, v2, s[60:61]
	global_store_dword v249, v2, s[58:59] offset:256
	v_cvt_pk_bf16_f32 v5, v247, v5
	v_cvt_pk_bf16_f32 v151, v151, v248
	v_cndmask_b32_e64 v5, v151, v5, s[60:61]
	global_store_dword v249, v5, s[58:59] offset:384
	s_waitcnt vmcnt(39)
	v_lshlrev_b32_e32 v250, 16, v184
	v_mul_f32_e32 v249, v138, v13
	v_fma_f32 v240, -v17, v249, v250
	v_and_b32_e32 v250, 0xffff0000, v184
	v_mul_f32_e32 v249, v122, v13
	v_fma_f32 v241, -v17, v249, v250
	v_lshlrev_b32_e32 v250, 16, v185
	v_mul_f32_e32 v249, v106, v13
	v_fma_f32 v242, -v17, v249, v250
	v_and_b32_e32 v250, 0xffff0000, v185
	v_mul_f32_e32 v249, v90, v13
	v_fma_f32 v243, -v17, v249, v250
	v_lshlrev_b32_e32 v250, 16, v186
	v_mul_f32_e32 v249, v74, v13
	v_fma_f32 v245, -v17, v249, v250
	v_and_b32_e32 v250, 0xffff0000, v186
	v_mul_f32_e32 v249, v58, v13
	v_fma_f32 v246, -v17, v249, v250
	v_lshlrev_b32_e32 v250, 16, v187
	v_mul_f32_e32 v249, v42, v13
	v_fma_f32 v247, -v17, v249, v250
	v_and_b32_e32 v250, 0xffff0000, v187
	v_mul_f32_e32 v249, v26, v13
	v_fma_f32 v248, -v17, v249, v250
	v_mul_f32_e32 v251, v241, v241
	v_fmac_f32_e32 v251, v240, v240
	v_fmac_f32_e32 v251, v242, v242
	v_fmac_f32_e32 v251, v243, v243
	v_fmac_f32_e32 v251, v245, v245
	v_fmac_f32_e32 v251, v246, v246
	v_fmac_f32_e32 v251, v247, v247
	v_fmac_f32_e32 v251, v248, v248
	s_nop 1
	v_add_f32_dpp v251, v251, v251 quad_perm:[1,0,3,2] row_mask:0xf bank_mask:0xf bound_ctrl:1
	s_nop 1
	v_add_f32_dpp v251, v251, v251 quad_perm:[2,3,0,1] row_mask:0xf bank_mask:0xf bound_ctrl:1
	s_nop 1
	v_add_f32_dpp v251, v251, v251 row_half_mirror row_mask:0xf bank_mask:0xf bound_ctrl:1
	s_nop 1
	v_add_f32_dpp v251, v251, v251 row_mirror row_mask:0xf bank_mask:0xf bound_ctrl:1
	ds_bpermute_b32 v252, v0, v251
	s_waitcnt lgkmcnt(0)
	v_add_f32_e32 v251, v251, v252
	v_fmamk_f32 v251, v251, 0x3b800000, v238
	v_mul_f32_e32 v252, 0x4f800000, v251
	v_cmp_gt_f32_e32 vcc, s24, v251
	s_nop 1
	v_cndmask_b32_e32 v251, v251, v252, vcc
	v_sqrt_f32_e32 v252, v251
	s_nop 0
	v_add_u32_e32 v249, -1, v252
	v_fma_f32 v250, -v249, v252, v251
	v_cmp_ge_f32_e64 s[6:7], 0, v250
	v_add_u32_e32 v250, 1, v252
	s_nop 0
	v_cndmask_b32_e64 v249, v252, v249, s[6:7]
	v_fma_f32 v252, -v250, v252, v251
	v_cmp_lt_f32_e64 s[6:7], 0, v252
	s_nop 1
	v_cndmask_b32_e64 v252, v249, v250, s[6:7]
	v_mul_f32_e32 v249, 0x37800000, v252
	v_cndmask_b32_e32 v252, v252, v249, vcc
	v_cmp_class_f32_e32 vcc, v251, v239
	s_nop 1
	v_cndmask_b32_e32 v251, v252, v251, vcc
	v_div_scale_f32 v252, s[2:3], v251, v251, 1.0
	v_rcp_f32_e32 v249, v252
	s_nop 0
	v_fma_f32 v250, -v252, v249, 1.0
	v_fmac_f32_e32 v249, v250, v249
	v_div_scale_f32 v250, vcc, 1.0, v251, 1.0
	v_mul_f32_e32 v253, v250, v249
	v_fma_f32 v213, -v252, v253, v250
	v_fmac_f32_e32 v253, v213, v249
	v_fma_f32 v252, -v252, v253, v250
	v_div_fmas_f32 v252, v252, v249, v253
	v_div_fixup_f32 v253, v252, v251, 1.0
	v_mul_f32_e32 v240, v240, v253
	v_mul_f32_e32 v241, v241, v253
	v_mul_f32_e32 v242, v242, v253
	v_mul_f32_e32 v243, v243, v253
	v_mul_f32_e32 v245, v245, v253
	v_mul_f32_e32 v246, v246, v253
	v_mul_f32_e32 v247, v247, v253
	v_mul_f32_e32 v248, v248, v253
	v_mul_f32_e32 v240, v224, v240
	v_mul_f32_e32 v241, v225, v241
	v_mul_f32_e32 v242, v226, v242
	v_mul_f32_e32 v243, v227, v243
	v_mul_f32_e32 v245, v228, v245
	v_mul_f32_e32 v246, v229, v246
	v_mul_f32_e32 v247, v230, v247
	v_mul_f32_e32 v248, v231, v248
	v_add_u32_e32 v249, 0x10000, v212
	v_mov_b32_dpp v232, v240 quad_perm:[1,0,3,2] row_mask:0xf bank_mask:0xf bound_ctrl:1
	v_mov_b32_dpp v233, v241 quad_perm:[1,0,3,2] row_mask:0xf bank_mask:0xf bound_ctrl:1
	v_mov_b32_dpp v234, v242 quad_perm:[1,0,3,2] row_mask:0xf bank_mask:0xf bound_ctrl:1
	v_mov_b32_dpp v235, v243 quad_perm:[1,0,3,2] row_mask:0xf bank_mask:0xf bound_ctrl:1
	v_mov_b32_dpp v2, v245 quad_perm:[1,0,3,2] row_mask:0xf bank_mask:0xf bound_ctrl:1
	v_mov_b32_dpp v3, v246 quad_perm:[1,0,3,2] row_mask:0xf bank_mask:0xf bound_ctrl:1
	v_mov_b32_dpp v5, v247 quad_perm:[1,0,3,2] row_mask:0xf bank_mask:0xf bound_ctrl:1
	v_mov_b32_dpp v151, v248 quad_perm:[1,0,3,2] row_mask:0xf bank_mask:0xf bound_ctrl:1
	v_cvt_pk_bf16_f32 v232, v240, v232
	v_cvt_pk_bf16_f32 v233, v233, v241
	v_cndmask_b32_e64 v232, v233, v232, s[60:61]
	global_store_dword v249, v232, s[58:59] offset:0
	v_cvt_pk_bf16_f32 v234, v242, v234
	v_cvt_pk_bf16_f32 v235, v235, v243
	v_cndmask_b32_e64 v234, v235, v234, s[60:61]
	global_store_dword v249, v234, s[58:59] offset:128
	v_cvt_pk_bf16_f32 v2, v245, v2
	v_cvt_pk_bf16_f32 v3, v3, v246
	v_cndmask_b32_e64 v2, v3, v2, s[60:61]
	global_store_dword v249, v2, s[58:59] offset:256
	v_cvt_pk_bf16_f32 v5, v247, v5
	v_cvt_pk_bf16_f32 v151, v151, v248
	v_cndmask_b32_e64 v5, v151, v5, s[60:61]
	global_store_dword v249, v5, s[58:59] offset:384
	s_waitcnt vmcnt(42)
	v_lshlrev_b32_e32 v250, 16, v188
	v_mul_f32_e32 v249, v139, v12
	v_fma_f32 v240, -v17, v249, v250
	v_and_b32_e32 v250, 0xffff0000, v188
	v_mul_f32_e32 v249, v123, v12
	v_fma_f32 v241, -v17, v249, v250
	v_lshlrev_b32_e32 v250, 16, v189
	v_mul_f32_e32 v249, v107, v12
	v_fma_f32 v242, -v17, v249, v250
	v_and_b32_e32 v250, 0xffff0000, v189
	v_mul_f32_e32 v249, v91, v12
	v_fma_f32 v243, -v17, v249, v250
	v_lshlrev_b32_e32 v250, 16, v190
	v_mul_f32_e32 v249, v75, v12
	v_fma_f32 v245, -v17, v249, v250
	v_and_b32_e32 v250, 0xffff0000, v190
	v_mul_f32_e32 v249, v59, v12
	v_fma_f32 v246, -v17, v249, v250
	v_lshlrev_b32_e32 v250, 16, v191
	v_mul_f32_e32 v249, v43, v12
	v_fma_f32 v247, -v17, v249, v250
	v_and_b32_e32 v250, 0xffff0000, v191
	v_mul_f32_e32 v249, v27, v12
	v_fma_f32 v248, -v17, v249, v250
	v_mul_f32_e32 v251, v241, v241
	v_fmac_f32_e32 v251, v240, v240
	v_fmac_f32_e32 v251, v242, v242
	v_fmac_f32_e32 v251, v243, v243
	v_fmac_f32_e32 v251, v245, v245
	v_fmac_f32_e32 v251, v246, v246
	v_fmac_f32_e32 v251, v247, v247
	v_fmac_f32_e32 v251, v248, v248
	s_nop 1
	v_add_f32_dpp v251, v251, v251 quad_perm:[1,0,3,2] row_mask:0xf bank_mask:0xf bound_ctrl:1
	s_nop 1
	v_add_f32_dpp v251, v251, v251 quad_perm:[2,3,0,1] row_mask:0xf bank_mask:0xf bound_ctrl:1
	s_nop 1
	v_add_f32_dpp v251, v251, v251 row_half_mirror row_mask:0xf bank_mask:0xf bound_ctrl:1
	s_nop 1
	v_add_f32_dpp v251, v251, v251 row_mirror row_mask:0xf bank_mask:0xf bound_ctrl:1
	ds_bpermute_b32 v252, v0, v251
	s_waitcnt lgkmcnt(0)
	v_add_f32_e32 v251, v251, v252
	v_fmamk_f32 v251, v251, 0x3b800000, v238
	v_mul_f32_e32 v252, 0x4f800000, v251
	v_cmp_gt_f32_e32 vcc, s24, v251
	s_nop 1
	v_cndmask_b32_e32 v251, v251, v252, vcc
	v_sqrt_f32_e32 v252, v251
	s_nop 0
	v_add_u32_e32 v249, -1, v252
	v_fma_f32 v250, -v249, v252, v251
	v_cmp_ge_f32_e64 s[6:7], 0, v250
	v_add_u32_e32 v250, 1, v252
	s_nop 0
	v_cndmask_b32_e64 v249, v252, v249, s[6:7]
	v_fma_f32 v252, -v250, v252, v251
	v_cmp_lt_f32_e64 s[6:7], 0, v252
	s_nop 1
	v_cndmask_b32_e64 v252, v249, v250, s[6:7]
	v_mul_f32_e32 v249, 0x37800000, v252
	v_cndmask_b32_e32 v252, v252, v249, vcc
	v_cmp_class_f32_e32 vcc, v251, v239
	s_nop 1
	v_cndmask_b32_e32 v251, v252, v251, vcc
	v_div_scale_f32 v252, s[2:3], v251, v251, 1.0
	v_rcp_f32_e32 v249, v252
	s_nop 0
	v_fma_f32 v250, -v252, v249, 1.0
	v_fmac_f32_e32 v249, v250, v249
	v_div_scale_f32 v250, vcc, 1.0, v251, 1.0
	v_mul_f32_e32 v253, v250, v249
	v_fma_f32 v213, -v252, v253, v250
	v_fmac_f32_e32 v253, v213, v249
	v_fma_f32 v252, -v252, v253, v250
	v_div_fmas_f32 v252, v252, v249, v253
	v_div_fixup_f32 v253, v252, v251, 1.0
	v_mul_f32_e32 v240, v240, v253
	v_mul_f32_e32 v241, v241, v253
	v_mul_f32_e32 v242, v242, v253
	v_mul_f32_e32 v243, v243, v253
	v_mul_f32_e32 v245, v245, v253
	v_mul_f32_e32 v246, v246, v253
	v_mul_f32_e32 v247, v247, v253
	v_mul_f32_e32 v248, v248, v253
	v_mul_f32_e32 v240, v224, v240
	v_mul_f32_e32 v241, v225, v241
	v_mul_f32_e32 v242, v226, v242
	v_mul_f32_e32 v243, v227, v243
	v_mul_f32_e32 v245, v228, v245
	v_mul_f32_e32 v246, v229, v246
	v_mul_f32_e32 v247, v230, v247
	v_mul_f32_e32 v248, v231, v248
	v_add_u32_e32 v249, 0x11000, v212
	v_mov_b32_dpp v232, v240 quad_perm:[1,0,3,2] row_mask:0xf bank_mask:0xf bound_ctrl:1
	v_mov_b32_dpp v233, v241 quad_perm:[1,0,3,2] row_mask:0xf bank_mask:0xf bound_ctrl:1
	v_mov_b32_dpp v234, v242 quad_perm:[1,0,3,2] row_mask:0xf bank_mask:0xf bound_ctrl:1
	v_mov_b32_dpp v235, v243 quad_perm:[1,0,3,2] row_mask:0xf bank_mask:0xf bound_ctrl:1
	v_mov_b32_dpp v2, v245 quad_perm:[1,0,3,2] row_mask:0xf bank_mask:0xf bound_ctrl:1
	v_mov_b32_dpp v3, v246 quad_perm:[1,0,3,2] row_mask:0xf bank_mask:0xf bound_ctrl:1
	v_mov_b32_dpp v5, v247 quad_perm:[1,0,3,2] row_mask:0xf bank_mask:0xf bound_ctrl:1
	v_mov_b32_dpp v151, v248 quad_perm:[1,0,3,2] row_mask:0xf bank_mask:0xf bound_ctrl:1
	v_cvt_pk_bf16_f32 v232, v240, v232
	v_cvt_pk_bf16_f32 v233, v233, v241
	v_cndmask_b32_e64 v232, v233, v232, s[60:61]
	global_store_dword v249, v232, s[58:59] offset:0
	v_cvt_pk_bf16_f32 v234, v242, v234
	v_cvt_pk_bf16_f32 v235, v235, v243
	v_cndmask_b32_e64 v234, v235, v234, s[60:61]
	global_store_dword v249, v234, s[58:59] offset:128
	v_cvt_pk_bf16_f32 v2, v245, v2
	v_cvt_pk_bf16_f32 v3, v3, v246
	v_cndmask_b32_e64 v2, v3, v2, s[60:61]
	global_store_dword v249, v2, s[58:59] offset:256
	v_cvt_pk_bf16_f32 v5, v247, v5
	v_cvt_pk_bf16_f32 v151, v151, v248
	v_cndmask_b32_e64 v5, v151, v5, s[60:61]
	global_store_dword v249, v5, s[58:59] offset:384
	s_waitcnt vmcnt(45)
	v_lshlrev_b32_e32 v250, 16, v192
	v_mul_f32_e32 v249, v140, v11
	v_fma_f32 v240, -v17, v249, v250
	v_and_b32_e32 v250, 0xffff0000, v192
	v_mul_f32_e32 v249, v124, v11
	v_fma_f32 v241, -v17, v249, v250
	v_lshlrev_b32_e32 v250, 16, v193
	v_mul_f32_e32 v249, v108, v11
	v_fma_f32 v242, -v17, v249, v250
	v_and_b32_e32 v250, 0xffff0000, v193
	v_mul_f32_e32 v249, v92, v11
	v_fma_f32 v243, -v17, v249, v250
	v_lshlrev_b32_e32 v250, 16, v194
	v_mul_f32_e32 v249, v76, v11
	v_fma_f32 v245, -v17, v249, v250
	v_and_b32_e32 v250, 0xffff0000, v194
	v_mul_f32_e32 v249, v60, v11
	v_fma_f32 v246, -v17, v249, v250
	v_lshlrev_b32_e32 v250, 16, v195
	v_mul_f32_e32 v249, v44, v11
	v_fma_f32 v247, -v17, v249, v250
	v_and_b32_e32 v250, 0xffff0000, v195
	v_mul_f32_e32 v249, v28, v11
	v_fma_f32 v248, -v17, v249, v250
	v_mul_f32_e32 v251, v241, v241
	v_fmac_f32_e32 v251, v240, v240
	v_fmac_f32_e32 v251, v242, v242
	v_fmac_f32_e32 v251, v243, v243
	v_fmac_f32_e32 v251, v245, v245
	v_fmac_f32_e32 v251, v246, v246
	v_fmac_f32_e32 v251, v247, v247
	v_fmac_f32_e32 v251, v248, v248
	s_nop 1
	v_add_f32_dpp v251, v251, v251 quad_perm:[1,0,3,2] row_mask:0xf bank_mask:0xf bound_ctrl:1
	s_nop 1
	v_add_f32_dpp v251, v251, v251 quad_perm:[2,3,0,1] row_mask:0xf bank_mask:0xf bound_ctrl:1
	s_nop 1
	v_add_f32_dpp v251, v251, v251 row_half_mirror row_mask:0xf bank_mask:0xf bound_ctrl:1
	s_nop 1
	v_add_f32_dpp v251, v251, v251 row_mirror row_mask:0xf bank_mask:0xf bound_ctrl:1
	ds_bpermute_b32 v252, v0, v251
	s_waitcnt lgkmcnt(0)
	v_add_f32_e32 v251, v251, v252
	v_fmamk_f32 v251, v251, 0x3b800000, v238
	v_mul_f32_e32 v252, 0x4f800000, v251
	v_cmp_gt_f32_e32 vcc, s24, v251
	s_nop 1
	v_cndmask_b32_e32 v251, v251, v252, vcc
	v_sqrt_f32_e32 v252, v251
	s_nop 0
	v_add_u32_e32 v249, -1, v252
	v_fma_f32 v250, -v249, v252, v251
	v_cmp_ge_f32_e64 s[6:7], 0, v250
	v_add_u32_e32 v250, 1, v252
	s_nop 0
	v_cndmask_b32_e64 v249, v252, v249, s[6:7]
	v_fma_f32 v252, -v250, v252, v251
	v_cmp_lt_f32_e64 s[6:7], 0, v252
	s_nop 1
	v_cndmask_b32_e64 v252, v249, v250, s[6:7]
	v_mul_f32_e32 v249, 0x37800000, v252
	v_cndmask_b32_e32 v252, v252, v249, vcc
	v_cmp_class_f32_e32 vcc, v251, v239
	s_nop 1
	v_cndmask_b32_e32 v251, v252, v251, vcc
	v_div_scale_f32 v252, s[2:3], v251, v251, 1.0
	v_rcp_f32_e32 v249, v252
	s_nop 0
	v_fma_f32 v250, -v252, v249, 1.0
	v_fmac_f32_e32 v249, v250, v249
	v_div_scale_f32 v250, vcc, 1.0, v251, 1.0
	v_mul_f32_e32 v253, v250, v249
	v_fma_f32 v213, -v252, v253, v250
	v_fmac_f32_e32 v253, v213, v249
	v_fma_f32 v252, -v252, v253, v250
	v_div_fmas_f32 v252, v252, v249, v253
	v_div_fixup_f32 v253, v252, v251, 1.0
	v_mul_f32_e32 v240, v240, v253
	v_mul_f32_e32 v241, v241, v253
	v_mul_f32_e32 v242, v242, v253
	v_mul_f32_e32 v243, v243, v253
	v_mul_f32_e32 v245, v245, v253
	v_mul_f32_e32 v246, v246, v253
	v_mul_f32_e32 v247, v247, v253
	v_mul_f32_e32 v248, v248, v253
	v_mul_f32_e32 v240, v224, v240
	v_mul_f32_e32 v241, v225, v241
	v_mul_f32_e32 v242, v226, v242
	v_mul_f32_e32 v243, v227, v243
	v_mul_f32_e32 v245, v228, v245
	v_mul_f32_e32 v246, v229, v246
	v_mul_f32_e32 v247, v230, v247
	v_mul_f32_e32 v248, v231, v248
	v_add_u32_e32 v249, 0x12000, v212
	v_mov_b32_dpp v232, v240 quad_perm:[1,0,3,2] row_mask:0xf bank_mask:0xf bound_ctrl:1
	v_mov_b32_dpp v233, v241 quad_perm:[1,0,3,2] row_mask:0xf bank_mask:0xf bound_ctrl:1
	v_mov_b32_dpp v234, v242 quad_perm:[1,0,3,2] row_mask:0xf bank_mask:0xf bound_ctrl:1
	v_mov_b32_dpp v235, v243 quad_perm:[1,0,3,2] row_mask:0xf bank_mask:0xf bound_ctrl:1
	v_mov_b32_dpp v2, v245 quad_perm:[1,0,3,2] row_mask:0xf bank_mask:0xf bound_ctrl:1
	v_mov_b32_dpp v3, v246 quad_perm:[1,0,3,2] row_mask:0xf bank_mask:0xf bound_ctrl:1
	v_mov_b32_dpp v5, v247 quad_perm:[1,0,3,2] row_mask:0xf bank_mask:0xf bound_ctrl:1
	v_mov_b32_dpp v151, v248 quad_perm:[1,0,3,2] row_mask:0xf bank_mask:0xf bound_ctrl:1
	v_cvt_pk_bf16_f32 v232, v240, v232
	v_cvt_pk_bf16_f32 v233, v233, v241
	v_cndmask_b32_e64 v232, v233, v232, s[60:61]
	global_store_dword v249, v232, s[58:59] offset:0
	v_cvt_pk_bf16_f32 v234, v242, v234
	v_cvt_pk_bf16_f32 v235, v235, v243
	v_cndmask_b32_e64 v234, v235, v234, s[60:61]
	global_store_dword v249, v234, s[58:59] offset:128
	v_cvt_pk_bf16_f32 v2, v245, v2
	v_cvt_pk_bf16_f32 v3, v3, v246
	v_cndmask_b32_e64 v2, v3, v2, s[60:61]
	global_store_dword v249, v2, s[58:59] offset:256
	v_cvt_pk_bf16_f32 v5, v247, v5
	v_cvt_pk_bf16_f32 v151, v151, v248
	v_cndmask_b32_e64 v5, v151, v5, s[60:61]
	global_store_dword v249, v5, s[58:59] offset:384
	s_waitcnt vmcnt(48)
	v_lshlrev_b32_e32 v250, 16, v196
	v_mul_f32_e32 v249, v141, v10
	v_fma_f32 v240, -v17, v249, v250
	v_and_b32_e32 v250, 0xffff0000, v196
	v_mul_f32_e32 v249, v125, v10
	v_fma_f32 v241, -v17, v249, v250
	v_lshlrev_b32_e32 v250, 16, v197
	v_mul_f32_e32 v249, v109, v10
	v_fma_f32 v242, -v17, v249, v250
	v_and_b32_e32 v250, 0xffff0000, v197
	v_mul_f32_e32 v249, v93, v10
	v_fma_f32 v243, -v17, v249, v250
	v_lshlrev_b32_e32 v250, 16, v198
	v_mul_f32_e32 v249, v77, v10
	v_fma_f32 v245, -v17, v249, v250
	v_and_b32_e32 v250, 0xffff0000, v198
	v_mul_f32_e32 v249, v61, v10
	v_fma_f32 v246, -v17, v249, v250
	v_lshlrev_b32_e32 v250, 16, v199
	v_mul_f32_e32 v249, v45, v10
	v_fma_f32 v247, -v17, v249, v250
	v_and_b32_e32 v250, 0xffff0000, v199
	v_mul_f32_e32 v249, v29, v10
	v_fma_f32 v248, -v17, v249, v250
	v_mul_f32_e32 v251, v241, v241
	v_fmac_f32_e32 v251, v240, v240
	v_fmac_f32_e32 v251, v242, v242
	v_fmac_f32_e32 v251, v243, v243
	v_fmac_f32_e32 v251, v245, v245
	v_fmac_f32_e32 v251, v246, v246
	v_fmac_f32_e32 v251, v247, v247
	v_fmac_f32_e32 v251, v248, v248
	s_nop 1
	v_add_f32_dpp v251, v251, v251 quad_perm:[1,0,3,2] row_mask:0xf bank_mask:0xf bound_ctrl:1
	s_nop 1
	v_add_f32_dpp v251, v251, v251 quad_perm:[2,3,0,1] row_mask:0xf bank_mask:0xf bound_ctrl:1
	s_nop 1
	v_add_f32_dpp v251, v251, v251 row_half_mirror row_mask:0xf bank_mask:0xf bound_ctrl:1
	s_nop 1
	v_add_f32_dpp v251, v251, v251 row_mirror row_mask:0xf bank_mask:0xf bound_ctrl:1
	ds_bpermute_b32 v252, v0, v251
	s_waitcnt lgkmcnt(0)
	v_add_f32_e32 v251, v251, v252
	v_fmamk_f32 v251, v251, 0x3b800000, v238
	v_mul_f32_e32 v252, 0x4f800000, v251
	v_cmp_gt_f32_e32 vcc, s24, v251
	s_nop 1
	v_cndmask_b32_e32 v251, v251, v252, vcc
	v_sqrt_f32_e32 v252, v251
	s_nop 0
	v_add_u32_e32 v249, -1, v252
	v_fma_f32 v250, -v249, v252, v251
	v_cmp_ge_f32_e64 s[6:7], 0, v250
	v_add_u32_e32 v250, 1, v252
	s_nop 0
	v_cndmask_b32_e64 v249, v252, v249, s[6:7]
	v_fma_f32 v252, -v250, v252, v251
	v_cmp_lt_f32_e64 s[6:7], 0, v252
	s_nop 1
	v_cndmask_b32_e64 v252, v249, v250, s[6:7]
	v_mul_f32_e32 v249, 0x37800000, v252
	v_cndmask_b32_e32 v252, v252, v249, vcc
	v_cmp_class_f32_e32 vcc, v251, v239
	s_nop 1
	v_cndmask_b32_e32 v251, v252, v251, vcc
	v_div_scale_f32 v252, s[2:3], v251, v251, 1.0
	v_rcp_f32_e32 v249, v252
	s_nop 0
	v_fma_f32 v250, -v252, v249, 1.0
	v_fmac_f32_e32 v249, v250, v249
	v_div_scale_f32 v250, vcc, 1.0, v251, 1.0
	v_mul_f32_e32 v253, v250, v249
	v_fma_f32 v213, -v252, v253, v250
	v_fmac_f32_e32 v253, v213, v249
	v_fma_f32 v252, -v252, v253, v250
	v_div_fmas_f32 v252, v252, v249, v253
	v_div_fixup_f32 v253, v252, v251, 1.0
	v_mul_f32_e32 v240, v240, v253
	v_mul_f32_e32 v241, v241, v253
	v_mul_f32_e32 v242, v242, v253
	v_mul_f32_e32 v243, v243, v253
	v_mul_f32_e32 v245, v245, v253
	v_mul_f32_e32 v246, v246, v253
	v_mul_f32_e32 v247, v247, v253
	v_mul_f32_e32 v248, v248, v253
	v_mul_f32_e32 v240, v224, v240
	v_mul_f32_e32 v241, v225, v241
	v_mul_f32_e32 v242, v226, v242
	v_mul_f32_e32 v243, v227, v243
	v_mul_f32_e32 v245, v228, v245
	v_mul_f32_e32 v246, v229, v246
	v_mul_f32_e32 v247, v230, v247
	v_mul_f32_e32 v248, v231, v248
	v_add_u32_e32 v249, 0x13000, v212
	v_mov_b32_dpp v232, v240 quad_perm:[1,0,3,2] row_mask:0xf bank_mask:0xf bound_ctrl:1
	v_mov_b32_dpp v233, v241 quad_perm:[1,0,3,2] row_mask:0xf bank_mask:0xf bound_ctrl:1
	v_mov_b32_dpp v234, v242 quad_perm:[1,0,3,2] row_mask:0xf bank_mask:0xf bound_ctrl:1
	v_mov_b32_dpp v235, v243 quad_perm:[1,0,3,2] row_mask:0xf bank_mask:0xf bound_ctrl:1
	v_mov_b32_dpp v2, v245 quad_perm:[1,0,3,2] row_mask:0xf bank_mask:0xf bound_ctrl:1
	v_mov_b32_dpp v3, v246 quad_perm:[1,0,3,2] row_mask:0xf bank_mask:0xf bound_ctrl:1
	v_mov_b32_dpp v5, v247 quad_perm:[1,0,3,2] row_mask:0xf bank_mask:0xf bound_ctrl:1
	v_mov_b32_dpp v151, v248 quad_perm:[1,0,3,2] row_mask:0xf bank_mask:0xf bound_ctrl:1
	v_cvt_pk_bf16_f32 v232, v240, v232
	v_cvt_pk_bf16_f32 v233, v233, v241
	v_cndmask_b32_e64 v232, v233, v232, s[60:61]
	global_store_dword v249, v232, s[58:59] offset:0
	v_cvt_pk_bf16_f32 v234, v242, v234
	v_cvt_pk_bf16_f32 v235, v235, v243
	v_cndmask_b32_e64 v234, v235, v234, s[60:61]
	global_store_dword v249, v234, s[58:59] offset:128
	v_cvt_pk_bf16_f32 v2, v245, v2
	v_cvt_pk_bf16_f32 v3, v3, v246
	v_cndmask_b32_e64 v2, v3, v2, s[60:61]
	global_store_dword v249, v2, s[58:59] offset:256
	v_cvt_pk_bf16_f32 v5, v247, v5
	v_cvt_pk_bf16_f32 v151, v151, v248
	v_cndmask_b32_e64 v5, v151, v5, s[60:61]
	global_store_dword v249, v5, s[58:59] offset:384
	s_waitcnt vmcnt(51)
	v_lshlrev_b32_e32 v250, 16, v200
	v_mul_f32_e32 v249, v142, v9
	v_fma_f32 v240, -v17, v249, v250
	v_and_b32_e32 v250, 0xffff0000, v200
	v_mul_f32_e32 v249, v126, v9
	v_fma_f32 v241, -v17, v249, v250
	v_lshlrev_b32_e32 v250, 16, v201
	v_mul_f32_e32 v249, v110, v9
	v_fma_f32 v242, -v17, v249, v250
	v_and_b32_e32 v250, 0xffff0000, v201
	v_mul_f32_e32 v249, v94, v9
	v_fma_f32 v243, -v17, v249, v250
	v_lshlrev_b32_e32 v250, 16, v202
	v_mul_f32_e32 v249, v78, v9
	v_fma_f32 v245, -v17, v249, v250
	v_and_b32_e32 v250, 0xffff0000, v202
	v_mul_f32_e32 v249, v62, v9
	v_fma_f32 v246, -v17, v249, v250
	v_lshlrev_b32_e32 v250, 16, v203
	v_mul_f32_e32 v249, v46, v9
	v_fma_f32 v247, -v17, v249, v250
	v_and_b32_e32 v250, 0xffff0000, v203
	v_mul_f32_e32 v249, v30, v9
	v_fma_f32 v248, -v17, v249, v250
	v_mul_f32_e32 v251, v241, v241
	v_fmac_f32_e32 v251, v240, v240
	v_fmac_f32_e32 v251, v242, v242
	v_fmac_f32_e32 v251, v243, v243
	v_fmac_f32_e32 v251, v245, v245
	v_fmac_f32_e32 v251, v246, v246
	v_fmac_f32_e32 v251, v247, v247
	v_fmac_f32_e32 v251, v248, v248
	s_nop 1
	v_add_f32_dpp v251, v251, v251 quad_perm:[1,0,3,2] row_mask:0xf bank_mask:0xf bound_ctrl:1
	s_nop 1
	v_add_f32_dpp v251, v251, v251 quad_perm:[2,3,0,1] row_mask:0xf bank_mask:0xf bound_ctrl:1
	s_nop 1
	v_add_f32_dpp v251, v251, v251 row_half_mirror row_mask:0xf bank_mask:0xf bound_ctrl:1
	s_nop 1
	v_add_f32_dpp v251, v251, v251 row_mirror row_mask:0xf bank_mask:0xf bound_ctrl:1
	ds_bpermute_b32 v252, v0, v251
	s_waitcnt lgkmcnt(0)
	v_add_f32_e32 v251, v251, v252
	v_fmamk_f32 v251, v251, 0x3b800000, v238
	v_mul_f32_e32 v252, 0x4f800000, v251
	v_cmp_gt_f32_e32 vcc, s24, v251
	s_nop 1
	v_cndmask_b32_e32 v251, v251, v252, vcc
	v_sqrt_f32_e32 v252, v251
	s_nop 0
	v_add_u32_e32 v249, -1, v252
	v_fma_f32 v250, -v249, v252, v251
	v_cmp_ge_f32_e64 s[6:7], 0, v250
	v_add_u32_e32 v250, 1, v252
	s_nop 0
	v_cndmask_b32_e64 v249, v252, v249, s[6:7]
	v_fma_f32 v252, -v250, v252, v251
	v_cmp_lt_f32_e64 s[6:7], 0, v252
	s_nop 1
	v_cndmask_b32_e64 v252, v249, v250, s[6:7]
	v_mul_f32_e32 v249, 0x37800000, v252
	v_cndmask_b32_e32 v252, v252, v249, vcc
	v_cmp_class_f32_e32 vcc, v251, v239
	s_nop 1
	v_cndmask_b32_e32 v251, v252, v251, vcc
	v_div_scale_f32 v252, s[2:3], v251, v251, 1.0
	v_rcp_f32_e32 v249, v252
	s_nop 0
	v_fma_f32 v250, -v252, v249, 1.0
	v_fmac_f32_e32 v249, v250, v249
	v_div_scale_f32 v250, vcc, 1.0, v251, 1.0
	v_mul_f32_e32 v253, v250, v249
	v_fma_f32 v213, -v252, v253, v250
	v_fmac_f32_e32 v253, v213, v249
	v_fma_f32 v252, -v252, v253, v250
	v_div_fmas_f32 v252, v252, v249, v253
	v_div_fixup_f32 v253, v252, v251, 1.0
	v_mul_f32_e32 v240, v240, v253
	v_mul_f32_e32 v241, v241, v253
	v_mul_f32_e32 v242, v242, v253
	v_mul_f32_e32 v243, v243, v253
	v_mul_f32_e32 v245, v245, v253
	v_mul_f32_e32 v246, v246, v253
	v_mul_f32_e32 v247, v247, v253
	v_mul_f32_e32 v248, v248, v253
	v_mul_f32_e32 v240, v224, v240
	v_mul_f32_e32 v241, v225, v241
	v_mul_f32_e32 v242, v226, v242
	v_mul_f32_e32 v243, v227, v243
	v_mul_f32_e32 v245, v228, v245
	v_mul_f32_e32 v246, v229, v246
	v_mul_f32_e32 v247, v230, v247
	v_mul_f32_e32 v248, v231, v248
	v_add_u32_e32 v249, 0x18000, v212
	v_mov_b32_dpp v232, v240 quad_perm:[1,0,3,2] row_mask:0xf bank_mask:0xf bound_ctrl:1
	v_mov_b32_dpp v233, v241 quad_perm:[1,0,3,2] row_mask:0xf bank_mask:0xf bound_ctrl:1
	v_mov_b32_dpp v234, v242 quad_perm:[1,0,3,2] row_mask:0xf bank_mask:0xf bound_ctrl:1
	v_mov_b32_dpp v235, v243 quad_perm:[1,0,3,2] row_mask:0xf bank_mask:0xf bound_ctrl:1
	v_mov_b32_dpp v2, v245 quad_perm:[1,0,3,2] row_mask:0xf bank_mask:0xf bound_ctrl:1
	v_mov_b32_dpp v3, v246 quad_perm:[1,0,3,2] row_mask:0xf bank_mask:0xf bound_ctrl:1
	v_mov_b32_dpp v5, v247 quad_perm:[1,0,3,2] row_mask:0xf bank_mask:0xf bound_ctrl:1
	v_mov_b32_dpp v151, v248 quad_perm:[1,0,3,2] row_mask:0xf bank_mask:0xf bound_ctrl:1
	v_cvt_pk_bf16_f32 v232, v240, v232
	v_cvt_pk_bf16_f32 v233, v233, v241
	v_cndmask_b32_e64 v232, v233, v232, s[60:61]
	global_store_dword v249, v232, s[58:59] offset:0
	v_cvt_pk_bf16_f32 v234, v242, v234
	v_cvt_pk_bf16_f32 v235, v235, v243
	v_cndmask_b32_e64 v234, v235, v234, s[60:61]
	global_store_dword v249, v234, s[58:59] offset:128
	v_cvt_pk_bf16_f32 v2, v245, v2
	v_cvt_pk_bf16_f32 v3, v3, v246
	v_cndmask_b32_e64 v2, v3, v2, s[60:61]
	global_store_dword v249, v2, s[58:59] offset:256
	v_cvt_pk_bf16_f32 v5, v247, v5
	v_cvt_pk_bf16_f32 v151, v151, v248
	v_cndmask_b32_e64 v5, v151, v5, s[60:61]
	global_store_dword v249, v5, s[58:59] offset:384
	s_waitcnt vmcnt(54)
	v_lshlrev_b32_e32 v250, 16, v204
	v_mul_f32_e32 v249, v143, v8
	v_fma_f32 v240, -v17, v249, v250
	v_and_b32_e32 v250, 0xffff0000, v204
	v_mul_f32_e32 v249, v127, v8
	v_fma_f32 v241, -v17, v249, v250
	v_lshlrev_b32_e32 v250, 16, v205
	v_mul_f32_e32 v249, v111, v8
	v_fma_f32 v242, -v17, v249, v250
	v_and_b32_e32 v250, 0xffff0000, v205
	v_mul_f32_e32 v249, v95, v8
	v_fma_f32 v243, -v17, v249, v250
	v_lshlrev_b32_e32 v250, 16, v206
	v_mul_f32_e32 v249, v79, v8
	v_fma_f32 v245, -v17, v249, v250
	v_and_b32_e32 v250, 0xffff0000, v206
	v_mul_f32_e32 v249, v63, v8
	v_fma_f32 v246, -v17, v249, v250
	v_lshlrev_b32_e32 v250, 16, v207
	v_mul_f32_e32 v249, v47, v8
	v_fma_f32 v247, -v17, v249, v250
	v_and_b32_e32 v250, 0xffff0000, v207
	v_mul_f32_e32 v249, v31, v8
	v_fma_f32 v248, -v17, v249, v250
	v_mul_f32_e32 v251, v241, v241
	v_fmac_f32_e32 v251, v240, v240
	v_fmac_f32_e32 v251, v242, v242
	v_fmac_f32_e32 v251, v243, v243
	v_fmac_f32_e32 v251, v245, v245
	v_fmac_f32_e32 v251, v246, v246
	v_fmac_f32_e32 v251, v247, v247
	v_fmac_f32_e32 v251, v248, v248
	s_nop 1
	v_add_f32_dpp v251, v251, v251 quad_perm:[1,0,3,2] row_mask:0xf bank_mask:0xf bound_ctrl:1
	s_nop 1
	v_add_f32_dpp v251, v251, v251 quad_perm:[2,3,0,1] row_mask:0xf bank_mask:0xf bound_ctrl:1
	s_nop 1
	v_add_f32_dpp v251, v251, v251 row_half_mirror row_mask:0xf bank_mask:0xf bound_ctrl:1
	s_nop 1
	v_add_f32_dpp v251, v251, v251 row_mirror row_mask:0xf bank_mask:0xf bound_ctrl:1
	ds_bpermute_b32 v252, v0, v251
	s_waitcnt lgkmcnt(0)
	v_add_f32_e32 v251, v251, v252
	v_fmamk_f32 v251, v251, 0x3b800000, v238
	v_mul_f32_e32 v252, 0x4f800000, v251
	v_cmp_gt_f32_e32 vcc, s24, v251
	s_nop 1
	v_cndmask_b32_e32 v251, v251, v252, vcc
	v_sqrt_f32_e32 v252, v251
	s_nop 0
	v_add_u32_e32 v249, -1, v252
	v_fma_f32 v250, -v249, v252, v251
	v_cmp_ge_f32_e64 s[6:7], 0, v250
	v_add_u32_e32 v250, 1, v252
	s_nop 0
	v_cndmask_b32_e64 v249, v252, v249, s[6:7]
	v_fma_f32 v252, -v250, v252, v251
	v_cmp_lt_f32_e64 s[6:7], 0, v252
	s_nop 1
	v_cndmask_b32_e64 v252, v249, v250, s[6:7]
	v_mul_f32_e32 v249, 0x37800000, v252
	v_cndmask_b32_e32 v252, v252, v249, vcc
	v_cmp_class_f32_e32 vcc, v251, v239
	s_nop 1
	v_cndmask_b32_e32 v251, v252, v251, vcc
	v_div_scale_f32 v252, s[2:3], v251, v251, 1.0
	v_rcp_f32_e32 v249, v252
	s_nop 0
	v_fma_f32 v250, -v252, v249, 1.0
	v_fmac_f32_e32 v249, v250, v249
	v_div_scale_f32 v250, vcc, 1.0, v251, 1.0
	v_mul_f32_e32 v253, v250, v249
	v_fma_f32 v213, -v252, v253, v250
	v_fmac_f32_e32 v253, v213, v249
	v_fma_f32 v252, -v252, v253, v250
	v_div_fmas_f32 v252, v252, v249, v253
	v_div_fixup_f32 v253, v252, v251, 1.0
	v_mul_f32_e32 v240, v240, v253
	v_mul_f32_e32 v241, v241, v253
	v_mul_f32_e32 v242, v242, v253
	v_mul_f32_e32 v243, v243, v253
	v_mul_f32_e32 v245, v245, v253
	v_mul_f32_e32 v246, v246, v253
	v_mul_f32_e32 v247, v247, v253
	v_mul_f32_e32 v248, v248, v253
	v_mul_f32_e32 v240, v224, v240
	v_mul_f32_e32 v241, v225, v241
	v_mul_f32_e32 v242, v226, v242
	v_mul_f32_e32 v243, v227, v243
	v_mul_f32_e32 v245, v228, v245
	v_mul_f32_e32 v246, v229, v246
	v_mul_f32_e32 v247, v230, v247
	v_mul_f32_e32 v248, v231, v248
	v_add_u32_e32 v249, 0x19000, v212
	v_mov_b32_dpp v232, v240 quad_perm:[1,0,3,2] row_mask:0xf bank_mask:0xf bound_ctrl:1
	v_mov_b32_dpp v233, v241 quad_perm:[1,0,3,2] row_mask:0xf bank_mask:0xf bound_ctrl:1
	v_mov_b32_dpp v234, v242 quad_perm:[1,0,3,2] row_mask:0xf bank_mask:0xf bound_ctrl:1
	v_mov_b32_dpp v235, v243 quad_perm:[1,0,3,2] row_mask:0xf bank_mask:0xf bound_ctrl:1
	v_mov_b32_dpp v2, v245 quad_perm:[1,0,3,2] row_mask:0xf bank_mask:0xf bound_ctrl:1
	v_mov_b32_dpp v3, v246 quad_perm:[1,0,3,2] row_mask:0xf bank_mask:0xf bound_ctrl:1
	v_mov_b32_dpp v5, v247 quad_perm:[1,0,3,2] row_mask:0xf bank_mask:0xf bound_ctrl:1
	v_mov_b32_dpp v151, v248 quad_perm:[1,0,3,2] row_mask:0xf bank_mask:0xf bound_ctrl:1
	v_cvt_pk_bf16_f32 v232, v240, v232
	v_cvt_pk_bf16_f32 v233, v233, v241
	v_cndmask_b32_e64 v232, v233, v232, s[60:61]
	global_store_dword v249, v232, s[58:59] offset:0
	v_cvt_pk_bf16_f32 v234, v242, v234
	v_cvt_pk_bf16_f32 v235, v235, v243
	v_cndmask_b32_e64 v234, v235, v234, s[60:61]
	global_store_dword v249, v234, s[58:59] offset:128
	v_cvt_pk_bf16_f32 v2, v245, v2
	v_cvt_pk_bf16_f32 v3, v3, v246
	v_cndmask_b32_e64 v2, v3, v2, s[60:61]
	global_store_dword v249, v2, s[58:59] offset:256
	v_cvt_pk_bf16_f32 v5, v247, v5
	v_cvt_pk_bf16_f32 v151, v151, v248
	v_cndmask_b32_e64 v5, v151, v5, s[60:61]
	global_store_dword v249, v5, s[58:59] offset:384
	s_waitcnt vmcnt(57)
	v_lshlrev_b32_e32 v250, 16, v216
	v_mul_f32_e32 v249, v144, v7
	v_fma_f32 v240, -v17, v249, v250
	v_and_b32_e32 v250, 0xffff0000, v216
	v_mul_f32_e32 v249, v128, v7
	v_fma_f32 v241, -v17, v249, v250
	v_lshlrev_b32_e32 v250, 16, v217
	v_mul_f32_e32 v249, v112, v7
	v_fma_f32 v242, -v17, v249, v250
	v_and_b32_e32 v250, 0xffff0000, v217
	v_mul_f32_e32 v249, v96, v7
	v_fma_f32 v243, -v17, v249, v250
	v_lshlrev_b32_e32 v250, 16, v218
	v_mul_f32_e32 v249, v80, v7
	v_fma_f32 v245, -v17, v249, v250
	v_and_b32_e32 v250, 0xffff0000, v218
	v_mul_f32_e32 v249, v64, v7
	v_fma_f32 v246, -v17, v249, v250
	v_lshlrev_b32_e32 v250, 16, v219
	v_mul_f32_e32 v249, v48, v7
	v_fma_f32 v247, -v17, v249, v250
	v_and_b32_e32 v250, 0xffff0000, v219
	v_mul_f32_e32 v249, v32, v7
	v_fma_f32 v248, -v17, v249, v250
	v_mul_f32_e32 v251, v241, v241
	v_fmac_f32_e32 v251, v240, v240
	v_fmac_f32_e32 v251, v242, v242
	v_fmac_f32_e32 v251, v243, v243
	v_fmac_f32_e32 v251, v245, v245
	v_fmac_f32_e32 v251, v246, v246
	v_fmac_f32_e32 v251, v247, v247
	v_fmac_f32_e32 v251, v248, v248
	s_nop 1
	v_add_f32_dpp v251, v251, v251 quad_perm:[1,0,3,2] row_mask:0xf bank_mask:0xf bound_ctrl:1
	s_nop 1
	v_add_f32_dpp v251, v251, v251 quad_perm:[2,3,0,1] row_mask:0xf bank_mask:0xf bound_ctrl:1
	s_nop 1
	v_add_f32_dpp v251, v251, v251 row_half_mirror row_mask:0xf bank_mask:0xf bound_ctrl:1
	s_nop 1
	v_add_f32_dpp v251, v251, v251 row_mirror row_mask:0xf bank_mask:0xf bound_ctrl:1
	ds_bpermute_b32 v252, v0, v251
	s_waitcnt lgkmcnt(0)
	v_add_f32_e32 v251, v251, v252
	v_fmamk_f32 v251, v251, 0x3b800000, v238
	v_mul_f32_e32 v252, 0x4f800000, v251
	v_cmp_gt_f32_e32 vcc, s24, v251
	s_nop 1
	v_cndmask_b32_e32 v251, v251, v252, vcc
	v_sqrt_f32_e32 v252, v251
	s_nop 0
	v_add_u32_e32 v249, -1, v252
	v_fma_f32 v250, -v249, v252, v251
	v_cmp_ge_f32_e64 s[6:7], 0, v250
	v_add_u32_e32 v250, 1, v252
	s_nop 0
	v_cndmask_b32_e64 v249, v252, v249, s[6:7]
	v_fma_f32 v252, -v250, v252, v251
	v_cmp_lt_f32_e64 s[6:7], 0, v252
	s_nop 1
	v_cndmask_b32_e64 v252, v249, v250, s[6:7]
	v_mul_f32_e32 v249, 0x37800000, v252
	v_cndmask_b32_e32 v252, v252, v249, vcc
	v_cmp_class_f32_e32 vcc, v251, v239
	s_nop 1
	v_cndmask_b32_e32 v251, v252, v251, vcc
	v_div_scale_f32 v252, s[2:3], v251, v251, 1.0
	v_rcp_f32_e32 v249, v252
	s_nop 0
	v_fma_f32 v250, -v252, v249, 1.0
	v_fmac_f32_e32 v249, v250, v249
	v_div_scale_f32 v250, vcc, 1.0, v251, 1.0
	v_mul_f32_e32 v253, v250, v249
	v_fma_f32 v213, -v252, v253, v250
	v_fmac_f32_e32 v253, v213, v249
	v_fma_f32 v252, -v252, v253, v250
	v_div_fmas_f32 v252, v252, v249, v253
	v_div_fixup_f32 v253, v252, v251, 1.0
	v_mul_f32_e32 v240, v240, v253
	v_mul_f32_e32 v241, v241, v253
	v_mul_f32_e32 v242, v242, v253
	v_mul_f32_e32 v243, v243, v253
	v_mul_f32_e32 v245, v245, v253
	v_mul_f32_e32 v246, v246, v253
	v_mul_f32_e32 v247, v247, v253
	v_mul_f32_e32 v248, v248, v253
	v_mul_f32_e32 v240, v224, v240
	v_mul_f32_e32 v241, v225, v241
	v_mul_f32_e32 v242, v226, v242
	v_mul_f32_e32 v243, v227, v243
	v_mul_f32_e32 v245, v228, v245
	v_mul_f32_e32 v246, v229, v246
	v_mul_f32_e32 v247, v230, v247
	v_mul_f32_e32 v248, v231, v248
	v_add_u32_e32 v249, 0x1a000, v212
	v_mov_b32_dpp v232, v240 quad_perm:[1,0,3,2] row_mask:0xf bank_mask:0xf bound_ctrl:1
	v_mov_b32_dpp v233, v241 quad_perm:[1,0,3,2] row_mask:0xf bank_mask:0xf bound_ctrl:1
	v_mov_b32_dpp v234, v242 quad_perm:[1,0,3,2] row_mask:0xf bank_mask:0xf bound_ctrl:1
	v_mov_b32_dpp v235, v243 quad_perm:[1,0,3,2] row_mask:0xf bank_mask:0xf bound_ctrl:1
	v_mov_b32_dpp v2, v245 quad_perm:[1,0,3,2] row_mask:0xf bank_mask:0xf bound_ctrl:1
	v_mov_b32_dpp v3, v246 quad_perm:[1,0,3,2] row_mask:0xf bank_mask:0xf bound_ctrl:1
	v_mov_b32_dpp v5, v247 quad_perm:[1,0,3,2] row_mask:0xf bank_mask:0xf bound_ctrl:1
	v_mov_b32_dpp v151, v248 quad_perm:[1,0,3,2] row_mask:0xf bank_mask:0xf bound_ctrl:1
	v_cvt_pk_bf16_f32 v232, v240, v232
	v_cvt_pk_bf16_f32 v233, v233, v241
	v_cndmask_b32_e64 v232, v233, v232, s[60:61]
	global_store_dword v249, v232, s[58:59] offset:0
	v_cvt_pk_bf16_f32 v234, v242, v234
	v_cvt_pk_bf16_f32 v235, v235, v243
	v_cndmask_b32_e64 v234, v235, v234, s[60:61]
	global_store_dword v249, v234, s[58:59] offset:128
	v_cvt_pk_bf16_f32 v2, v245, v2
	v_cvt_pk_bf16_f32 v3, v3, v246
	v_cndmask_b32_e64 v2, v3, v2, s[60:61]
	global_store_dword v249, v2, s[58:59] offset:256
	v_cvt_pk_bf16_f32 v5, v247, v5
	v_cvt_pk_bf16_f32 v151, v151, v248
	v_cndmask_b32_e64 v5, v151, v5, s[60:61]
	global_store_dword v249, v5, s[58:59] offset:384
	s_waitcnt vmcnt(60)
	v_lshlrev_b32_e32 v250, 16, v220
	v_mul_f32_e32 v249, v145, v6
	v_fma_f32 v240, -v17, v249, v250
	v_and_b32_e32 v250, 0xffff0000, v220
	v_mul_f32_e32 v249, v129, v6
	v_fma_f32 v241, -v17, v249, v250
	v_lshlrev_b32_e32 v250, 16, v221
	v_mul_f32_e32 v249, v113, v6
	v_fma_f32 v242, -v17, v249, v250
	v_and_b32_e32 v250, 0xffff0000, v221
	v_mul_f32_e32 v249, v97, v6
	v_fma_f32 v243, -v17, v249, v250
	v_lshlrev_b32_e32 v250, 16, v222
	v_mul_f32_e32 v249, v81, v6
	v_fma_f32 v245, -v17, v249, v250
	v_and_b32_e32 v250, 0xffff0000, v222
	v_mul_f32_e32 v249, v65, v6
	v_fma_f32 v246, -v17, v249, v250
	v_lshlrev_b32_e32 v250, 16, v223
	v_mul_f32_e32 v249, v49, v6
	v_fma_f32 v247, -v17, v249, v250
	v_and_b32_e32 v250, 0xffff0000, v223
	v_mul_f32_e32 v249, v33, v6
	v_fma_f32 v248, -v17, v249, v250
	v_mul_f32_e32 v251, v241, v241
	v_fmac_f32_e32 v251, v240, v240
	v_fmac_f32_e32 v251, v242, v242
	v_fmac_f32_e32 v251, v243, v243
	v_fmac_f32_e32 v251, v245, v245
	v_fmac_f32_e32 v251, v246, v246
	v_fmac_f32_e32 v251, v247, v247
	v_fmac_f32_e32 v251, v248, v248
	s_nop 1
	v_add_f32_dpp v251, v251, v251 quad_perm:[1,0,3,2] row_mask:0xf bank_mask:0xf bound_ctrl:1
	s_nop 1
	v_add_f32_dpp v251, v251, v251 quad_perm:[2,3,0,1] row_mask:0xf bank_mask:0xf bound_ctrl:1
	s_nop 1
	v_add_f32_dpp v251, v251, v251 row_half_mirror row_mask:0xf bank_mask:0xf bound_ctrl:1
	s_nop 1
	v_add_f32_dpp v251, v251, v251 row_mirror row_mask:0xf bank_mask:0xf bound_ctrl:1
	ds_bpermute_b32 v252, v0, v251
	s_waitcnt lgkmcnt(0)
	v_add_f32_e32 v251, v251, v252
	v_fmamk_f32 v251, v251, 0x3b800000, v238
	v_mul_f32_e32 v252, 0x4f800000, v251
	v_cmp_gt_f32_e32 vcc, s24, v251
	s_nop 1
	v_cndmask_b32_e32 v251, v251, v252, vcc
	v_sqrt_f32_e32 v252, v251
	s_nop 0
	v_add_u32_e32 v249, -1, v252
	v_fma_f32 v250, -v249, v252, v251
	v_cmp_ge_f32_e64 s[6:7], 0, v250
	v_add_u32_e32 v250, 1, v252
	s_nop 0
	v_cndmask_b32_e64 v249, v252, v249, s[6:7]
	v_fma_f32 v252, -v250, v252, v251
	v_cmp_lt_f32_e64 s[6:7], 0, v252
	s_nop 1
	v_cndmask_b32_e64 v252, v249, v250, s[6:7]
	v_mul_f32_e32 v249, 0x37800000, v252
	v_cndmask_b32_e32 v252, v252, v249, vcc
	v_cmp_class_f32_e32 vcc, v251, v239
	s_nop 1
	v_cndmask_b32_e32 v251, v252, v251, vcc
	v_div_scale_f32 v252, s[2:3], v251, v251, 1.0
	v_rcp_f32_e32 v249, v252
	s_nop 0
	v_fma_f32 v250, -v252, v249, 1.0
	v_fmac_f32_e32 v249, v250, v249
	v_div_scale_f32 v250, vcc, 1.0, v251, 1.0
	v_mul_f32_e32 v253, v250, v249
	v_fma_f32 v213, -v252, v253, v250
	v_fmac_f32_e32 v253, v213, v249
	v_fma_f32 v252, -v252, v253, v250
	v_div_fmas_f32 v252, v252, v249, v253
	v_div_fixup_f32 v253, v252, v251, 1.0
	v_mul_f32_e32 v240, v240, v253
	v_mul_f32_e32 v241, v241, v253
	v_mul_f32_e32 v242, v242, v253
	v_mul_f32_e32 v243, v243, v253
	v_mul_f32_e32 v245, v245, v253
	v_mul_f32_e32 v246, v246, v253
	v_mul_f32_e32 v247, v247, v253
	v_mul_f32_e32 v248, v248, v253
	v_mul_f32_e32 v240, v224, v240
	v_mul_f32_e32 v241, v225, v241
	v_mul_f32_e32 v242, v226, v242
	v_mul_f32_e32 v243, v227, v243
	v_mul_f32_e32 v245, v228, v245
	v_mul_f32_e32 v246, v229, v246
	v_mul_f32_e32 v247, v230, v247
	v_mul_f32_e32 v248, v231, v248
	v_add_u32_e32 v249, 0x1b000, v212
	v_mov_b32_dpp v232, v240 quad_perm:[1,0,3,2] row_mask:0xf bank_mask:0xf bound_ctrl:1
	v_mov_b32_dpp v233, v241 quad_perm:[1,0,3,2] row_mask:0xf bank_mask:0xf bound_ctrl:1
	v_mov_b32_dpp v234, v242 quad_perm:[1,0,3,2] row_mask:0xf bank_mask:0xf bound_ctrl:1
	v_mov_b32_dpp v235, v243 quad_perm:[1,0,3,2] row_mask:0xf bank_mask:0xf bound_ctrl:1
	v_mov_b32_dpp v2, v245 quad_perm:[1,0,3,2] row_mask:0xf bank_mask:0xf bound_ctrl:1
	v_mov_b32_dpp v3, v246 quad_perm:[1,0,3,2] row_mask:0xf bank_mask:0xf bound_ctrl:1
	v_mov_b32_dpp v5, v247 quad_perm:[1,0,3,2] row_mask:0xf bank_mask:0xf bound_ctrl:1
	v_mov_b32_dpp v151, v248 quad_perm:[1,0,3,2] row_mask:0xf bank_mask:0xf bound_ctrl:1
	v_cvt_pk_bf16_f32 v232, v240, v232
	v_cvt_pk_bf16_f32 v233, v233, v241
	v_cndmask_b32_e64 v232, v233, v232, s[60:61]
	global_store_dword v249, v232, s[58:59] offset:0
	v_cvt_pk_bf16_f32 v234, v242, v234
	v_cvt_pk_bf16_f32 v235, v235, v243
	v_cndmask_b32_e64 v234, v235, v234, s[60:61]
	global_store_dword v249, v234, s[58:59] offset:128
	v_cvt_pk_bf16_f32 v2, v245, v2
	v_cvt_pk_bf16_f32 v3, v3, v246
	v_cndmask_b32_e64 v2, v3, v2, s[60:61]
	global_store_dword v249, v2, s[58:59] offset:256
	v_cvt_pk_bf16_f32 v5, v247, v5
	v_cvt_pk_bf16_f32 v151, v151, v248
	v_cndmask_b32_e64 v5, v151, v5, s[60:61]
	global_store_dword v249, v5, s[58:59] offset:384
	s_branch .Lep_done
.Lep_mode0:
	v_lshlrev_b32_e32 v3, 12, v237
	v_lshl_add_u32 v3, v210, 4, v3
	v_cvt_pk_bf16_f32 v152, v130, v114
	v_cvt_pk_bf16_f32 v153, v98, v82
	v_cvt_pk_bf16_f32 v154, v66, v50
	v_cvt_pk_bf16_f32 v155, v34, v18
	global_store_dwordx4 v3, v[152:155], s[56:57]
	v_add_u32_e32 v3, 0x2000, v3
	v_mul_f32_e32 v249, v131, v150
	v_mul_f32_e32 v250, v115, v150
	v_cvt_pk_bf16_f32 v156, v249, v250
	v_mul_f32_e32 v249, v99, v150
	v_mul_f32_e32 v250, v83, v150
	v_cvt_pk_bf16_f32 v157, v249, v250
	v_mul_f32_e32 v249, v67, v150
	v_mul_f32_e32 v250, v51, v150
	v_cvt_pk_bf16_f32 v158, v249, v250
	v_mul_f32_e32 v249, v35, v150
	v_mul_f32_e32 v250, v19, v150
	v_cvt_pk_bf16_f32 v159, v249, v250
	global_store_dwordx4 v3, v[156:159], s[56:57]
	v_add_u32_e32 v3, 0x2000, v3
	v_mul_f32_e32 v249, v132, v149
	v_mul_f32_e32 v250, v116, v149
	v_cvt_pk_bf16_f32 v160, v249, v250
	v_mul_f32_e32 v249, v100, v149
	v_mul_f32_e32 v250, v84, v149
	v_cvt_pk_bf16_f32 v161, v249, v250
	v_mul_f32_e32 v249, v68, v149
	v_mul_f32_e32 v250, v52, v149
	v_cvt_pk_bf16_f32 v162, v249, v250
	v_mul_f32_e32 v249, v36, v149
	v_mul_f32_e32 v250, v20, v149
	v_cvt_pk_bf16_f32 v163, v249, v250
	global_store_dwordx4 v3, v[160:163], s[56:57]
	v_add_u32_e32 v3, 0x2000, v3
	v_mul_f32_e32 v249, v133, v148
	v_mul_f32_e32 v250, v117, v148
	v_cvt_pk_bf16_f32 v164, v249, v250
	v_mul_f32_e32 v249, v101, v148
	v_mul_f32_e32 v250, v85, v148
	v_cvt_pk_bf16_f32 v165, v249, v250
	v_mul_f32_e32 v249, v69, v148
	v_mul_f32_e32 v250, v53, v148
	v_cvt_pk_bf16_f32 v166, v249, v250
	v_mul_f32_e32 v249, v37, v148
	v_mul_f32_e32 v250, v21, v148
	v_cvt_pk_bf16_f32 v167, v249, v250
	global_store_dwordx4 v3, v[164:167], s[56:57]
	v_add_u32_e32 v3, 0x2000, v3
	v_mul_f32_e32 v249, v134, v147
	v_mul_f32_e32 v250, v118, v147
	v_cvt_pk_bf16_f32 v152, v249, v250
	v_mul_f32_e32 v249, v102, v147
	v_mul_f32_e32 v250, v86, v147
	v_cvt_pk_bf16_f32 v153, v249, v250
	v_mul_f32_e32 v249, v70, v147
	v_mul_f32_e32 v250, v54, v147
	v_cvt_pk_bf16_f32 v154, v249, v250
	v_mul_f32_e32 v249, v38, v147
	v_mul_f32_e32 v250, v22, v147
	v_cvt_pk_bf16_f32 v155, v249, v250
	global_store_dwordx4 v3, v[152:155], s[56:57]
	v_add_u32_e32 v3, 0x2000, v3
	v_mul_f32_e32 v249, v135, v146
	v_mul_f32_e32 v250, v119, v146
	v_cvt_pk_bf16_f32 v156, v249, v250
	v_mul_f32_e32 v249, v103, v146
	v_mul_f32_e32 v250, v87, v146
	v_cvt_pk_bf16_f32 v157, v249, v250
	v_mul_f32_e32 v249, v71, v146
	v_mul_f32_e32 v250, v55, v146
	v_cvt_pk_bf16_f32 v158, v249, v250
	v_mul_f32_e32 v249, v39, v146
	v_mul_f32_e32 v250, v23, v146
	v_cvt_pk_bf16_f32 v159, v249, v250
	global_store_dwordx4 v3, v[156:159], s[56:57]
	v_add_u32_e32 v3, 0x2000, v3
	v_mul_f32_e32 v249, v136, v15
	v_mul_f32_e32 v250, v120, v15
	v_cvt_pk_bf16_f32 v160, v249, v250
	v_mul_f32_e32 v249, v104, v15
	v_mul_f32_e32 v250, v88, v15
	v_cvt_pk_bf16_f32 v161, v249, v250
	v_mul_f32_e32 v249, v72, v15
	v_mul_f32_e32 v250, v56, v15
	v_cvt_pk_bf16_f32 v162, v249, v250
	v_mul_f32_e32 v249, v40, v15
	v_mul_f32_e32 v250, v24, v15
	v_cvt_pk_bf16_f32 v163, v249, v250
	global_store_dwordx4 v3, v[160:163], s[56:57]
	v_add_u32_e32 v3, 0x2000, v3
	v_mul_f32_e32 v249, v137, v14
	v_mul_f32_e32 v250, v121, v14
	v_cvt_pk_bf16_f32 v164, v249, v250
	v_mul_f32_e32 v249, v105, v14
	v_mul_f32_e32 v250, v89, v14
	v_cvt_pk_bf16_f32 v165, v249, v250
	v_mul_f32_e32 v249, v73, v14
	v_mul_f32_e32 v250, v57, v14
	v_cvt_pk_bf16_f32 v166, v249, v250
	v_mul_f32_e32 v249, v41, v14
	v_mul_f32_e32 v250, v25, v14
	v_cvt_pk_bf16_f32 v167, v249, v250
	global_store_dwordx4 v3, v[164:167], s[56:57]
	v_add_u32_e32 v3, 0x2000, v3
	v_mul_f32_e32 v249, v138, v13
	v_mul_f32_e32 v250, v122, v13
	v_cvt_pk_bf16_f32 v152, v249, v250
	v_mul_f32_e32 v249, v106, v13
	v_mul_f32_e32 v250, v90, v13
	v_cvt_pk_bf16_f32 v153, v249, v250
	v_mul_f32_e32 v249, v74, v13
	v_mul_f32_e32 v250, v58, v13
	v_cvt_pk_bf16_f32 v154, v249, v250
	v_mul_f32_e32 v249, v42, v13
	v_mul_f32_e32 v250, v26, v13
	v_cvt_pk_bf16_f32 v155, v249, v250
	global_store_dwordx4 v3, v[152:155], s[56:57]
	v_add_u32_e32 v3, 0x2000, v3
	v_mul_f32_e32 v249, v139, v12
	v_mul_f32_e32 v250, v123, v12
	v_cvt_pk_bf16_f32 v156, v249, v250
	v_mul_f32_e32 v249, v107, v12
	v_mul_f32_e32 v250, v91, v12
	v_cvt_pk_bf16_f32 v157, v249, v250
	v_mul_f32_e32 v249, v75, v12
	v_mul_f32_e32 v250, v59, v12
	v_cvt_pk_bf16_f32 v158, v249, v250
	v_mul_f32_e32 v249, v43, v12
	v_mul_f32_e32 v250, v27, v12
	v_cvt_pk_bf16_f32 v159, v249, v250
	global_store_dwordx4 v3, v[156:159], s[56:57]
	v_add_u32_e32 v3, 0x2000, v3
	v_mul_f32_e32 v249, v140, v11
	v_mul_f32_e32 v250, v124, v11
	v_cvt_pk_bf16_f32 v160, v249, v250
	v_mul_f32_e32 v249, v108, v11
	v_mul_f32_e32 v250, v92, v11
	v_cvt_pk_bf16_f32 v161, v249, v250
	v_mul_f32_e32 v249, v76, v11
	v_mul_f32_e32 v250, v60, v11
	v_cvt_pk_bf16_f32 v162, v249, v250
	v_mul_f32_e32 v249, v44, v11
	v_mul_f32_e32 v250, v28, v11
	v_cvt_pk_bf16_f32 v163, v249, v250
	global_store_dwordx4 v3, v[160:163], s[56:57]
	v_add_u32_e32 v3, 0x2000, v3
	v_mul_f32_e32 v249, v141, v10
	v_mul_f32_e32 v250, v125, v10
	v_cvt_pk_bf16_f32 v164, v249, v250
	v_mul_f32_e32 v249, v109, v10
	v_mul_f32_e32 v250, v93, v10
	v_cvt_pk_bf16_f32 v165, v249, v250
	v_mul_f32_e32 v249, v77, v10
	v_mul_f32_e32 v250, v61, v10
	v_cvt_pk_bf16_f32 v166, v249, v250
	v_mul_f32_e32 v249, v45, v10
	v_mul_f32_e32 v250, v29, v10
	v_cvt_pk_bf16_f32 v167, v249, v250
	global_store_dwordx4 v3, v[164:167], s[56:57]
	v_add_u32_e32 v3, 0x2000, v3
	v_mul_f32_e32 v249, v142, v9
	v_mul_f32_e32 v250, v126, v9
	v_cvt_pk_bf16_f32 v152, v249, v250
	v_mul_f32_e32 v249, v110, v9
	v_mul_f32_e32 v250, v94, v9
	v_cvt_pk_bf16_f32 v153, v249, v250
	v_mul_f32_e32 v249, v78, v9
	v_mul_f32_e32 v250, v62, v9
	v_cvt_pk_bf16_f32 v154, v249, v250
	v_mul_f32_e32 v249, v46, v9
	v_mul_f32_e32 v250, v30, v9
	v_cvt_pk_bf16_f32 v155, v249, v250
	global_store_dwordx4 v3, v[152:155], s[56:57]
	v_add_u32_e32 v3, 0x2000, v3
	v_mul_f32_e32 v249, v143, v8
	v_mul_f32_e32 v250, v127, v8
	v_cvt_pk_bf16_f32 v156, v249, v250
	v_mul_f32_e32 v249, v111, v8
	v_mul_f32_e32 v250, v95, v8
	v_cvt_pk_bf16_f32 v157, v249, v250
	v_mul_f32_e32 v249, v79, v8
	v_mul_f32_e32 v250, v63, v8
	v_cvt_pk_bf16_f32 v158, v249, v250
	v_mul_f32_e32 v249, v47, v8
	v_mul_f32_e32 v250, v31, v8
	v_cvt_pk_bf16_f32 v159, v249, v250
	global_store_dwordx4 v3, v[156:159], s[56:57]
	v_add_u32_e32 v3, 0x2000, v3
	v_mul_f32_e32 v249, v144, v7
	v_mul_f32_e32 v250, v128, v7
	v_cvt_pk_bf16_f32 v160, v249, v250
	v_mul_f32_e32 v249, v112, v7
	v_mul_f32_e32 v250, v96, v7
	v_cvt_pk_bf16_f32 v161, v249, v250
	v_mul_f32_e32 v249, v80, v7
	v_mul_f32_e32 v250, v64, v7
	v_cvt_pk_bf16_f32 v162, v249, v250
	v_mul_f32_e32 v249, v48, v7
	v_mul_f32_e32 v250, v32, v7
	v_cvt_pk_bf16_f32 v163, v249, v250
	global_store_dwordx4 v3, v[160:163], s[56:57]
	v_add_u32_e32 v3, 0x2000, v3
	v_mul_f32_e32 v249, v145, v6
	v_mul_f32_e32 v250, v129, v6
	v_cvt_pk_bf16_f32 v164, v249, v250
	v_mul_f32_e32 v249, v113, v6
	v_mul_f32_e32 v250, v97, v6
	v_cvt_pk_bf16_f32 v165, v249, v250
	v_mul_f32_e32 v249, v81, v6
	v_mul_f32_e32 v250, v65, v6
	v_cvt_pk_bf16_f32 v166, v249, v250
	v_mul_f32_e32 v249, v49, v6
	v_mul_f32_e32 v250, v33, v6
	v_cvt_pk_bf16_f32 v167, v249, v250
	global_store_dwordx4 v3, v[164:167], s[56:57]
	s_branch .Lep_done
